# first K-iteration of each GEMM K-loop peeled with C=0 MFMAs, per-tile accumulator zero-init removed (on top of flips removal)
# speedup vs baseline: 1.0139x; 1.0139x over previous
; #define PG8_STAGE(bufoff, gbase, voff) do { _Pragma("unroll") for (int _i = 0; _i < 2; ++_i) \
;         __builtin_amdgcn_global_load_lds((const unsigned*)((const char*)(gbase) + (voff)[_i]), (PG8_LAS unsigned*)(lds + (bufoff) + ldsw + _i * 8192), 16, 0, 0); } while (0)
; #define PG8_LDA(dst, b, h) do { _Pragma("unroll") for (int m = 0; m < 4; ++m) _Pragma("unroll") for (int k = 0; k < 2; ++k) dst[m][k] = *(const PG8_LAS bf16x8*)(lds + PG8_SA(b, h) + aoff + m * 2048 + k * 1024); } while (0)
; #define PG8_LDB(dst, b, h) do { _Pragma("unroll") for (int n = 0; n < 2; ++n) _Pragma("unroll") for (int k = 0; k < 2; ++k) dst[n][k] = *(const PG8_LAS bf16x8*)(lds + PG8_SB(b, h) + boff + n * 2048 + k * 1024); } while (0)
; #define PG8_WAIT_V(n) asm volatile("s_waitcnt vmcnt(" #n ")" ::: "memory")
; #define PG8_WAIT_L(n) asm volatile("s_waitcnt lgkmcnt(" #n ")" ::: "memory")
; #define PG8_BAR __builtin_amdgcn_s_barrier()
; #define PG8_SCHED __builtin_amdgcn_sched_barrier(0)
; template <class Epi, class Sched, bool ALIGN_EPI = false, bool SP2 = false>
; __device__ __forceinline__ void gemm_phase(PG8_LAS unsigned char* lds, const Gemm g, const Sched& S, const Epi& E, const int tid) {
;     ...
;         const bool has_next = S.next(ui + 1, nxt);
;         const char* nA = has_next ? (const char*)g.A + (size_t)nxt.pm * tstep : cA; const char* nB = has_next ? (const char*)g.Bt + (size_t)nxt.pn * tstep : cB;
;         for (int t = 0; t < nt; t += 2) {
;             const bool last = (t == nt - 2);
;             const char* a1 = cA + (size_t)(t + 1) * kstep;
;             const char* a2 = last ? nA : cA + (size_t)(t + 2) * kstep; const char* b2 = last ? nB : cB + (size_t)(t + 2) * kstep;
;             const char* a3 = a2 + kstep; const char* b3 = b2 + kstep;
;             if (last && has_next) S.a_ready(nxt);
;             if constexpr (SP2) {
;             PG8_LDB(B0, 0, 0); PG8_LDB(B1, 0, 1); PG8_SCHED; PG8_LDA(At, 0, 0); PG8_STAGE(PG8_SA(1, 1), a1 + hstep, voffA);
;             PG8_WAIT_V(8); PG8_WAIT_L(0); PG8_BAR; PG8_MMA(0, 0, At, B0); PG8_MMA(0, 1, At, B1); PG8_BAR; PG8_SCHED;
;             PG8_LDA(At, 0, 1); PG8_STAGE(PG8_SB(0, 0), b2, voffB); PG8_STAGE(PG8_SB(0, 1), b2 + hstep, voffB); PG8_STAGE(PG8_SA(0, 0), a2, voffA);
;             PG8_WAIT_V(8); PG8_WAIT_L(0); PG8_BAR; PG8_MMA(1, 0, At, B0); PG8_MMA(1, 1, At, B1); PG8_BAR; PG8_SCHED;
.LBB0_98:
	s_ashr_i32 s13, s12, 31
	s_lshl_b64 s[14:15], s[12:13], 19
	s_add_u32 s14, s27, s14
	s_addc_u32 s15, s34, s15
	s_and_b64 s[16:17], s[2:3], exec
	s_cselect_b32 s13, s15, s19
	s_cselect_b32 s45, s14, s18
	s_ashr_i32 s11, s10, 31
	s_lshl_b64 s[16:17], s[10:11], 19
	s_add_u32 s16, s24, s16
	s_addc_u32 s17, s25, s17
	s_and_b64 s[22:23], s[2:3], exec
	s_cselect_b32 s11, s17, s21
	s_cselect_b32 s46, s16, s20
	s_add_u32 s18, s18, 0x40080
	s_addc_u32 s19, s19, 0
	s_add_u32 s47, s20, 0x100
	v_mov_b32_e32 v4, 0
	s_addc_u32 s48, s21, 0
	s_mov_b32 s49, -2
	s_add_u32 s20, s18, 0xfffc0080
	s_addc_u32 s21, s19, -1
	s_add_i32 s50, 0, 0x10000
	s_cmp_eq_u32 s49, 12
	s_cselect_b32 s23, s13, s21
	s_cselect_b32 s22, s45, s20
	s_cselect_b32 s21, s11, s48
	s_cselect_b32 s20, s46, s47
	s_add_i32 s52, 0, 0x14000
	v_add_u32_e32 v132, s50, v153
	v_add_u32_e32 v148, s52, v153
	ds_read_b128 v[116:119], v132
	ds_read_b128 v[120:123], v132 offset:1024
	ds_read_b128 v[124:127], v132 offset:2048
	ds_read_b128 v[132:135], v132 offset:3072
	ds_read_b128 v[178:181], v148
	ds_read_b128 v[182:185], v148 offset:1024
	ds_read_b128 v[186:189], v148 offset:2048
	ds_read_b128 v[190:193], v148 offset:3072
	v_lshl_add_u64 v[148:149], s[18:19], 0, v[172:173]
	s_add_i32 m0, s36, 0xc000
	ds_read_b128 v[194:197], v176
	ds_read_b128 v[198:201], v176 offset:1024
	ds_read_b128 v[202:205], v176 offset:2048
	ds_read_b128 v[206:209], v176 offset:3072
	ds_read_b128 v[210:213], v176 offset:4096
	ds_read_b128 v[214:217], v176 offset:5120
	ds_read_b128 v[218:221], v176 offset:6144
	ds_read_b128 v[222:225], v176 offset:7168
	global_load_lds_dwordx4 v[148:149], off
	v_lshl_add_u64 v[148:149], s[18:19], 0, v[174:175]
	s_add_i32 m0, s36, 0xe000
	s_nop 0
	global_load_lds_dwordx4 v[148:149], off
	s_waitcnt vmcnt(8)
	s_waitcnt lgkmcnt(0)
	s_barrier
	s_waitcnt lgkmcnt(0)
	v_mfma_f32_16x16x32_bf16 v[144:147], v[116:119], v[194:197], 0
	v_mfma_f32_16x16x32_bf16 v[140:143], v[124:127], v[194:197], 0
	v_mfma_f32_16x16x32_bf16 v[112:115], v[116:119], v[202:205], 0
	v_mfma_f32_16x16x32_bf16 v[108:111], v[124:127], v[202:205], 0
	v_mfma_f32_16x16x32_bf16 v[96:99], v[116:119], v[210:213], 0
	v_mfma_f32_16x16x32_bf16 v[92:95], v[124:127], v[210:213], 0
	v_mfma_f32_16x16x32_bf16 v[80:83], v[116:119], v[218:221], 0
	v_mfma_f32_16x16x32_bf16 v[76:79], v[124:127], v[218:221], 0
	v_mfma_f32_16x16x32_bf16 v[144:147], v[120:123], v[198:201], v[144:147]
	v_mfma_f32_16x16x32_bf16 v[140:143], v[132:135], v[198:201], v[140:143]
	v_mfma_f32_16x16x32_bf16 v[112:115], v[120:123], v[206:209], v[112:115]
	v_mfma_f32_16x16x32_bf16 v[108:111], v[132:135], v[206:209], v[108:111]
	v_mfma_f32_16x16x32_bf16 v[96:99], v[120:123], v[214:217], v[96:99]
	v_mfma_f32_16x16x32_bf16 v[92:95], v[132:135], v[214:217], v[92:95]
	v_mfma_f32_16x16x32_bf16 v[80:83], v[120:123], v[222:225], v[80:83]
	v_mfma_f32_16x16x32_bf16 v[76:79], v[132:135], v[222:225], v[76:79]
	v_mfma_f32_16x16x32_bf16 v[136:139], v[178:181], v[194:197], 0
	v_mfma_f32_16x16x32_bf16 v[128:131], v[186:189], v[194:197], 0
	v_mfma_f32_16x16x32_bf16 v[104:107], v[178:181], v[202:205], 0
	v_mfma_f32_16x16x32_bf16 v[100:103], v[186:189], v[202:205], 0
	v_mfma_f32_16x16x32_bf16 v[88:91], v[178:181], v[210:213], 0
	v_mfma_f32_16x16x32_bf16 v[84:87], v[186:189], v[210:213], 0
	v_mfma_f32_16x16x32_bf16 v[72:75], v[178:181], v[218:221], 0
	v_mfma_f32_16x16x32_bf16 v[68:71], v[186:189], v[218:221], 0
	v_mfma_f32_16x16x32_bf16 v[136:139], v[182:185], v[198:201], v[136:139]
	v_mfma_f32_16x16x32_bf16 v[128:131], v[190:193], v[198:201], v[128:131]
	v_mfma_f32_16x16x32_bf16 v[104:107], v[182:185], v[206:209], v[104:107]
	v_mfma_f32_16x16x32_bf16 v[100:103], v[190:193], v[206:209], v[100:103]
	v_mfma_f32_16x16x32_bf16 v[88:91], v[182:185], v[214:217], v[88:91]
	v_mfma_f32_16x16x32_bf16 v[84:87], v[190:193], v[214:217], v[84:87]
	v_mfma_f32_16x16x32_bf16 v[72:75], v[182:185], v[222:225], v[72:75]
	v_mfma_f32_16x16x32_bf16 v[68:71], v[190:193], v[222:225], v[68:71]
	s_barrier
	s_add_i32 s50, s50, s26
	v_lshl_add_u64 v[148:149], s[20:21], 0, v[168:169]
	s_mov_b32 m0, s50
	ds_read_b128 v[194:197], v176 offset:16384
	ds_read_b128 v[198:201], v176 offset:17408
	ds_read_b128 v[202:205], v176 offset:18432
	ds_read_b128 v[206:209], v176 offset:19456
	ds_read_b128 v[210:213], v176 offset:20480
	ds_read_b128 v[214:217], v176 offset:21504
	ds_read_b128 v[218:221], v176 offset:22528
	ds_read_b128 v[222:225], v176 offset:23552
	global_load_lds_dwordx4 v[148:149], off
	s_add_i32 m0, s50, 0x2000
	s_add_u32 s50, s20, 0x40000
	v_lshl_add_u64 v[150:151], s[20:21], 0, v[0:1]
	s_addc_u32 s51, s21, 0
	s_add_i32 s52, s52, s26
	global_load_lds_dwordx4 v[150:151], off
	v_lshl_add_u64 v[226:227], s[50:51], 0, v[168:169]
	s_mov_b32 m0, s52
	v_lshl_add_u64 v[238:239], s[22:23], 0, v[166:167]
	global_load_lds_dwordx4 v[226:227], off
	v_lshl_add_u64 v[226:227], s[50:51], 0, v[0:1]
	s_add_i32 m0, s52, 0x2000
	s_nop 0
	global_load_lds_dwordx4 v[226:227], off
	v_lshl_add_u64 v[226:227], s[22:23], 0, v[170:171]
	s_mov_b32 m0, s36
	s_nop 0
	global_load_lds_dwordx4 v[226:227], off
	s_mov_b32 m0, s37
	s_nop 0
	global_load_lds_dwordx4 v[238:239], off
	s_waitcnt vmcnt(8)
	s_waitcnt lgkmcnt(0)
	s_barrier
; #define PG8_STAGE(bufoff, gbase, voff) do { _Pragma("unroll") for (int _i = 0; _i < 2; ++_i) \
;         __builtin_amdgcn_global_load_lds((const unsigned*)((const char*)(gbase) + (voff)[_i]), (PG8_LAS unsigned*)(lds + (bufoff) + ldsw + _i * 8192), 16, 0, 0); } while (0)
; #define PG8_LDA(dst, b, h) do { _Pragma("unroll") for (int m = 0; m < 4; ++m) _Pragma("unroll") for (int k = 0; k < 2; ++k) dst[m][k] = *(const PG8_LAS bf16x8*)(lds + PG8_SA(b, h) + aoff + m * 2048 + k * 1024); } while (0)
; #define PG8_LDB(dst, b, h) do { _Pragma("unroll") for (int n = 0; n < 2; ++n) _Pragma("unroll") for (int k = 0; k < 2; ++k) dst[n][k] = *(const PG8_LAS bf16x8*)(lds + PG8_SB(b, h) + boff + n * 2048 + k * 1024); } while (0)
; #define PG8_MMA(ai, bj, At, Bt) do { __builtin_amdgcn_s_setprio(1); _Pragma("unroll") for (int m = 0; m < 4; ++m) _Pragma("unroll") for (int n = 0; n < 2; ++n) _Pragma("unroll") for (int k = 0; k < 2; ++k) \
;         acc[ai][bj][m][n] = __builtin_amdgcn_mfma_f32_16x16x32_bf16(Bt[n][k], At[m][k], acc[ai][bj][m][n], 0, 0, 0); __builtin_amdgcn_s_setprio(0); } while (0)
; #define PG8_WAIT_V(n) asm volatile("s_waitcnt vmcnt(" #n ")" ::: "memory")
; #define PG8_WAIT_L(n) asm volatile("s_waitcnt lgkmcnt(" #n ")" ::: "memory")
; #define PG8_BAR __builtin_amdgcn_s_barrier()
; #define PG8_SCHED __builtin_amdgcn_sched_barrier(0)
; template <class Epi, class Sched, bool ALIGN_EPI = false, bool SP2 = false>
; __device__ __forceinline__ void gemm_phase(PG8_LAS unsigned char* lds, const Gemm g, const Sched& S, const Epi& E, const int tid) {
;     ...
;             PG8_WAIT_V(8); PG8_WAIT_L(0); PG8_BAR; PG8_MMA(1, 0, At, B0); PG8_MMA(1, 1, At, B1); PG8_BAR; PG8_SCHED;
;             PG8_LDB(B0, 1, 0); PG8_LDB(B1, 1, 1); PG8_SCHED; PG8_LDA(At, 1, 0); PG8_STAGE(PG8_SA(0, 1), a2 + hstep, voffA);
;             PG8_WAIT_V(8); PG8_WAIT_L(0); PG8_BAR; PG8_MMA(0, 0, At, B0); PG8_MMA(0, 1, At, B1); PG8_BAR; PG8_SCHED;
;             PG8_LDA(At, 1, 1); PG8_STAGE(PG8_SB(1, 0), b3, voffB); PG8_STAGE(PG8_SB(1, 1), b3 + hstep, voffB); PG8_STAGE(PG8_SA(1, 0), a3, voffA);
	s_waitcnt lgkmcnt(0)
	v_mfma_f32_16x16x32_bf16 v[64:67], v[116:119], v[194:197], 0
	v_mfma_f32_16x16x32_bf16 v[60:63], v[124:127], v[194:197], 0
	v_mfma_f32_16x16x32_bf16 v[56:59], v[116:119], v[202:205], 0
	v_mfma_f32_16x16x32_bf16 v[48:51], v[124:127], v[202:205], 0
	v_mfma_f32_16x16x32_bf16 v[40:43], v[116:119], v[210:213], 0
	v_mfma_f32_16x16x32_bf16 v[32:35], v[124:127], v[210:213], 0
	v_mfma_f32_16x16x32_bf16 v[24:27], v[116:119], v[218:221], 0
	v_mfma_f32_16x16x32_bf16 v[16:19], v[124:127], v[218:221], 0
	v_mfma_f32_16x16x32_bf16 v[64:67], v[120:123], v[198:201], v[64:67]
	v_mfma_f32_16x16x32_bf16 v[60:63], v[132:135], v[198:201], v[60:63]
	v_mfma_f32_16x16x32_bf16 v[56:59], v[120:123], v[206:209], v[56:59]
	v_mfma_f32_16x16x32_bf16 v[48:51], v[132:135], v[206:209], v[48:51]
	v_mfma_f32_16x16x32_bf16 v[40:43], v[120:123], v[214:217], v[40:43]
	v_mfma_f32_16x16x32_bf16 v[32:35], v[132:135], v[214:217], v[32:35]
	v_mfma_f32_16x16x32_bf16 v[24:27], v[120:123], v[222:225], v[24:27]
	v_mfma_f32_16x16x32_bf16 v[16:19], v[132:135], v[222:225], v[16:19]
	v_mfma_f32_16x16x32_bf16 v[52:55], v[178:181], v[194:197], 0
	v_mfma_f32_16x16x32_bf16 v[44:47], v[186:189], v[194:197], 0
	v_mfma_f32_16x16x32_bf16 v[36:39], v[178:181], v[202:205], 0
	v_mfma_f32_16x16x32_bf16 v[28:31], v[186:189], v[202:205], 0
	v_mfma_f32_16x16x32_bf16 v[20:23], v[178:181], v[210:213], 0
	v_mfma_f32_16x16x32_bf16 v[12:15], v[186:189], v[210:213], 0
	v_mfma_f32_16x16x32_bf16 v[8:11], v[178:181], v[218:221], 0
	v_mfma_f32_16x16x32_bf16 v[4:7], v[186:189], v[218:221], 0
	v_mfma_f32_16x16x32_bf16 v[52:55], v[182:185], v[198:201], v[52:55]
	v_mfma_f32_16x16x32_bf16 v[44:47], v[190:193], v[198:201], v[44:47]
	v_mfma_f32_16x16x32_bf16 v[36:39], v[182:185], v[206:209], v[36:39]
	v_mfma_f32_16x16x32_bf16 v[28:31], v[190:193], v[206:209], v[28:31]
	v_mfma_f32_16x16x32_bf16 v[20:23], v[182:185], v[214:217], v[20:23]
	v_mfma_f32_16x16x32_bf16 v[12:15], v[190:193], v[214:217], v[12:15]
	v_mfma_f32_16x16x32_bf16 v[8:11], v[182:185], v[222:225], v[8:11]
	v_mfma_f32_16x16x32_bf16 v[4:7], v[190:193], v[222:225], v[4:7]
	s_barrier
	s_add_i32 s50, 0, 0x18000
	s_add_i32 s51, 0, 0x1c000
	v_add_u32_e32 v132, s50, v153
	v_add_u32_e32 v177, s51, v153
	ds_read_b128 v[116:119], v132
	ds_read_b128 v[120:123], v132 offset:1024
	ds_read_b128 v[124:127], v132 offset:2048
	ds_read_b128 v[132:135], v132 offset:3072
	ds_read_b128 v[178:181], v177
	ds_read_b128 v[182:185], v177 offset:1024
	ds_read_b128 v[186:189], v177 offset:2048
	ds_read_b128 v[190:193], v177 offset:3072
	s_add_u32 s22, s22, 0x40000
	s_addc_u32 s23, s23, 0
	s_mov_b32 m0, s38
	v_lshl_add_u64 v[240:241], s[22:23], 0, v[170:171]
	ds_read_b128 v[194:197], v176 offset:32768
	ds_read_b128 v[198:201], v176 offset:33792
	ds_read_b128 v[202:205], v176 offset:34816
	ds_read_b128 v[206:209], v176 offset:35840
	ds_read_b128 v[210:213], v176 offset:36864
	ds_read_b128 v[214:217], v176 offset:37888
	ds_read_b128 v[218:221], v176 offset:38912
	ds_read_b128 v[222:225], v176 offset:39936
	global_load_lds_dwordx4 v[240:241], off
	v_lshl_add_u64 v[240:241], s[22:23], 0, v[166:167]
	s_mov_b32 m0, s39
	s_nop 0
	global_load_lds_dwordx4 v[240:241], off
	s_waitcnt vmcnt(8)
	s_waitcnt lgkmcnt(0)
	s_barrier
	s_waitcnt lgkmcnt(0)
	v_mfma_f32_16x16x32_bf16 v[144:147], v[116:119], v[194:197], v[144:147]
	v_mfma_f32_16x16x32_bf16 v[140:143], v[124:127], v[194:197], v[140:143]
	v_mfma_f32_16x16x32_bf16 v[112:115], v[116:119], v[202:205], v[112:115]
	v_mfma_f32_16x16x32_bf16 v[108:111], v[124:127], v[202:205], v[108:111]
	v_mfma_f32_16x16x32_bf16 v[96:99], v[116:119], v[210:213], v[96:99]
	v_mfma_f32_16x16x32_bf16 v[92:95], v[124:127], v[210:213], v[92:95]
	v_mfma_f32_16x16x32_bf16 v[80:83], v[116:119], v[218:221], v[80:83]
	v_mfma_f32_16x16x32_bf16 v[76:79], v[124:127], v[218:221], v[76:79]
	v_mfma_f32_16x16x32_bf16 v[144:147], v[120:123], v[198:201], v[144:147]
	v_mfma_f32_16x16x32_bf16 v[140:143], v[132:135], v[198:201], v[140:143]
	v_mfma_f32_16x16x32_bf16 v[112:115], v[120:123], v[206:209], v[112:115]
	v_mfma_f32_16x16x32_bf16 v[108:111], v[132:135], v[206:209], v[108:111]
	v_mfma_f32_16x16x32_bf16 v[96:99], v[120:123], v[214:217], v[96:99]
	v_mfma_f32_16x16x32_bf16 v[92:95], v[132:135], v[214:217], v[92:95]
	v_mfma_f32_16x16x32_bf16 v[80:83], v[120:123], v[222:225], v[80:83]
	v_mfma_f32_16x16x32_bf16 v[76:79], v[132:135], v[222:225], v[76:79]
	v_mfma_f32_16x16x32_bf16 v[136:139], v[178:181], v[194:197], v[136:139]
	v_mfma_f32_16x16x32_bf16 v[128:131], v[186:189], v[194:197], v[128:131]
	v_mfma_f32_16x16x32_bf16 v[104:107], v[178:181], v[202:205], v[104:107]
	v_mfma_f32_16x16x32_bf16 v[100:103], v[186:189], v[202:205], v[100:103]
	v_mfma_f32_16x16x32_bf16 v[88:91], v[178:181], v[210:213], v[88:91]
	v_mfma_f32_16x16x32_bf16 v[84:87], v[186:189], v[210:213], v[84:87]
	v_mfma_f32_16x16x32_bf16 v[72:75], v[178:181], v[218:221], v[72:75]
	v_mfma_f32_16x16x32_bf16 v[68:71], v[186:189], v[218:221], v[68:71]
	v_mfma_f32_16x16x32_bf16 v[136:139], v[182:185], v[198:201], v[136:139]
	v_mfma_f32_16x16x32_bf16 v[128:131], v[190:193], v[198:201], v[128:131]
	v_mfma_f32_16x16x32_bf16 v[104:107], v[182:185], v[206:209], v[104:107]
	v_mfma_f32_16x16x32_bf16 v[100:103], v[190:193], v[206:209], v[100:103]
	v_mfma_f32_16x16x32_bf16 v[88:91], v[182:185], v[214:217], v[88:91]
	v_mfma_f32_16x16x32_bf16 v[84:87], v[190:193], v[214:217], v[84:87]
	v_mfma_f32_16x16x32_bf16 v[72:75], v[182:185], v[222:225], v[72:75]
	v_mfma_f32_16x16x32_bf16 v[68:71], v[190:193], v[222:225], v[68:71]
	s_barrier
; #define PG8_STAGE(bufoff, gbase, voff) do { _Pragma("unroll") for (int _i = 0; _i < 2; ++_i) \
;         __builtin_amdgcn_global_load_lds((const unsigned*)((const char*)(gbase) + (voff)[_i]), (PG8_LAS unsigned*)(lds + (bufoff) + ldsw + _i * 8192), 16, 0, 0); } while (0)
; #define PG8_LDA(dst, b, h) do { _Pragma("unroll") for (int m = 0; m < 4; ++m) _Pragma("unroll") for (int k = 0; k < 2; ++k) dst[m][k] = *(const PG8_LAS bf16x8*)(lds + PG8_SA(b, h) + aoff + m * 2048 + k * 1024); } while (0)
; #define PG8_MMA(ai, bj, At, Bt) do { __builtin_amdgcn_s_setprio(1); _Pragma("unroll") for (int m = 0; m < 4; ++m) _Pragma("unroll") for (int n = 0; n < 2; ++n) _Pragma("unroll") for (int k = 0; k < 2; ++k) \
;         acc[ai][bj][m][n] = __builtin_amdgcn_mfma_f32_16x16x32_bf16(Bt[n][k], At[m][k], acc[ai][bj][m][n], 0, 0, 0); __builtin_amdgcn_s_setprio(0); } while (0)
; #define PG8_WAIT_V(n) asm volatile("s_waitcnt vmcnt(" #n ")" ::: "memory")
; #define PG8_WAIT_L(n) asm volatile("s_waitcnt lgkmcnt(" #n ")" ::: "memory")
; #define PG8_BAR __builtin_amdgcn_s_barrier()
; #define PG8_SCHED __builtin_amdgcn_sched_barrier(0)
; template <class Epi, class Sched, bool ALIGN_EPI = false, bool SP2 = false>
; __device__ __forceinline__ void gemm_phase(PG8_LAS unsigned char* lds, const Gemm g, const Sched& S, const Epi& E, const int tid) {
;     ...
;             PG8_LDA(At, 1, 1); PG8_STAGE(PG8_SB(1, 0), b3, voffB); PG8_STAGE(PG8_SB(1, 1), b3 + hstep, voffB); PG8_STAGE(PG8_SA(1, 0), a3, voffA);
;             PG8_WAIT_V(8); PG8_WAIT_L(0); PG8_BAR; PG8_MMA(1, 0, At, B0); PG8_MMA(1, 1, At, B1); PG8_BAR; PG8_SCHED;
	s_add_i32 s22, s50, s26
	v_lshl_add_u64 v[148:149], v[148:149], 0, s[0:1]
	s_mov_b32 m0, s22
	ds_read_b128 v[194:197], v176 offset:49152
	ds_read_b128 v[198:201], v176 offset:50176
	ds_read_b128 v[202:205], v176 offset:51200
	ds_read_b128 v[206:209], v176 offset:52224
	ds_read_b128 v[210:213], v176 offset:53248
	ds_read_b128 v[214:217], v176 offset:54272
	ds_read_b128 v[218:221], v176 offset:55296
	ds_read_b128 v[222:225], v176 offset:56320
	global_load_lds_dwordx4 v[148:149], off
	s_add_i32 m0, s22, 0x2000
	s_add_u32 s20, s20, 0x40080
	v_lshl_add_u64 v[148:149], v[150:151], 0, s[0:1]
	s_addc_u32 s21, s21, 0
	s_add_i32 s22, s51, s26
	global_load_lds_dwordx4 v[148:149], off
	v_lshl_add_u64 v[148:149], s[20:21], 0, v[168:169]
	s_mov_b32 m0, s22
	s_nop 0
	global_load_lds_dwordx4 v[148:149], off
	v_lshl_add_u64 v[148:149], s[20:21], 0, v[0:1]
	s_add_i32 m0, s22, 0x2000
	s_nop 0
	global_load_lds_dwordx4 v[148:149], off
	v_lshl_add_u64 v[148:149], v[226:227], 0, s[0:1]
	s_mov_b32 m0, s40
	s_nop 0
	global_load_lds_dwordx4 v[148:149], off
	v_lshl_add_u64 v[148:149], v[238:239], 0, s[0:1]
	s_mov_b32 m0, s41
	s_nop 0
	global_load_lds_dwordx4 v[148:149], off
	s_waitcnt vmcnt(8)
	s_waitcnt lgkmcnt(0)
	s_barrier
	s_waitcnt lgkmcnt(0)
	v_mfma_f32_16x16x32_bf16 v[64:67], v[116:119], v[194:197], v[64:67]
	v_mfma_f32_16x16x32_bf16 v[60:63], v[124:127], v[194:197], v[60:63]
	v_mfma_f32_16x16x32_bf16 v[56:59], v[116:119], v[202:205], v[56:59]
	v_mfma_f32_16x16x32_bf16 v[48:51], v[124:127], v[202:205], v[48:51]
	v_mfma_f32_16x16x32_bf16 v[40:43], v[116:119], v[210:213], v[40:43]
	v_mfma_f32_16x16x32_bf16 v[32:35], v[124:127], v[210:213], v[32:35]
	v_mfma_f32_16x16x32_bf16 v[24:27], v[116:119], v[218:221], v[24:27]
	v_mfma_f32_16x16x32_bf16 v[16:19], v[124:127], v[218:221], v[16:19]
	v_mfma_f32_16x16x32_bf16 v[64:67], v[120:123], v[198:201], v[64:67]
	v_mfma_f32_16x16x32_bf16 v[60:63], v[132:135], v[198:201], v[60:63]
	v_mfma_f32_16x16x32_bf16 v[56:59], v[120:123], v[206:209], v[56:59]
	v_mfma_f32_16x16x32_bf16 v[48:51], v[132:135], v[206:209], v[48:51]
	v_mfma_f32_16x16x32_bf16 v[40:43], v[120:123], v[214:217], v[40:43]
	v_mfma_f32_16x16x32_bf16 v[32:35], v[132:135], v[214:217], v[32:35]
	v_mfma_f32_16x16x32_bf16 v[24:27], v[120:123], v[222:225], v[24:27]
	v_mfma_f32_16x16x32_bf16 v[16:19], v[132:135], v[222:225], v[16:19]
	v_mfma_f32_16x16x32_bf16 v[52:55], v[178:181], v[194:197], v[52:55]
	v_mfma_f32_16x16x32_bf16 v[44:47], v[186:189], v[194:197], v[44:47]
	v_mfma_f32_16x16x32_bf16 v[36:39], v[178:181], v[202:205], v[36:39]
	v_mfma_f32_16x16x32_bf16 v[28:31], v[186:189], v[202:205], v[28:31]
	v_mfma_f32_16x16x32_bf16 v[20:23], v[178:181], v[210:213], v[20:23]
	v_mfma_f32_16x16x32_bf16 v[12:15], v[186:189], v[210:213], v[12:15]
	v_mfma_f32_16x16x32_bf16 v[8:11], v[178:181], v[218:221], v[8:11]
	v_mfma_f32_16x16x32_bf16 v[4:7], v[186:189], v[218:221], v[4:7]
	v_mfma_f32_16x16x32_bf16 v[52:55], v[182:185], v[198:201], v[52:55]
	v_mfma_f32_16x16x32_bf16 v[44:47], v[190:193], v[198:201], v[44:47]
	v_mfma_f32_16x16x32_bf16 v[36:39], v[182:185], v[206:209], v[36:39]
	v_mfma_f32_16x16x32_bf16 v[28:31], v[190:193], v[206:209], v[28:31]
	v_mfma_f32_16x16x32_bf16 v[20:23], v[182:185], v[214:217], v[20:23]
	v_mfma_f32_16x16x32_bf16 v[12:15], v[190:193], v[214:217], v[12:15]
	v_mfma_f32_16x16x32_bf16 v[8:11], v[182:185], v[222:225], v[8:11]
	v_mfma_f32_16x16x32_bf16 v[4:7], v[190:193], v[222:225], v[4:7]
	s_barrier
	s_add_i32 s49, s49, 2
	s_add_u32 s18, s18, 0x100
	s_addc_u32 s19, s19, 0
	s_add_u32 s47, s47, 0x100
	s_addc_u32 s48, s48, 0
	s_cmp_gt_u32 s49, 13
	s_cbranch_scc0 .LBB0_99
	s_branch .Lpeel_exit0

; #define PG8_BAR __builtin_amdgcn_s_barrier()
; template <class Epi, class Sched, bool ALIGN_EPI = false, bool SP2 = false>
; __device__ __forceinline__ void gemm_phase(PG8_LAS unsigned char* lds, const Gemm g, const Sched& S, const Epi& E, const int tid) {
;     ...
;         if constexpr (ALIGN_EPI) { if (wr == 0) PG8_BAR; }
.Lpeel_exit0:
	s_and_b64 vcc, exec, s[8:9]
	s_cbranch_vccz .LBB0_102
	s_barrier

; #define PG8_STAGE(bufoff, gbase, voff) do { _Pragma("unroll") for (int _i = 0; _i < 2; ++_i) \
;         __builtin_amdgcn_global_load_lds((const unsigned*)((const char*)(gbase) + (voff)[_i]), (PG8_LAS unsigned*)(lds + (bufoff) + ldsw + _i * 8192), 16, 0, 0); } while (0)
; #define PG8_LDA(dst, b, h) do { _Pragma("unroll") for (int m = 0; m < 4; ++m) _Pragma("unroll") for (int k = 0; k < 2; ++k) dst[m][k] = *(const PG8_LAS bf16x8*)(lds + PG8_SA(b, h) + aoff + m * 2048 + k * 1024); } while (0)
; #define PG8_LDB(dst, b, h) do { _Pragma("unroll") for (int n = 0; n < 2; ++n) _Pragma("unroll") for (int k = 0; k < 2; ++k) dst[n][k] = *(const PG8_LAS bf16x8*)(lds + PG8_SB(b, h) + boff + n * 2048 + k * 1024); } while (0)
; #define PG8_WAIT_V(n) asm volatile("s_waitcnt vmcnt(" #n ")" ::: "memory")
; #define PG8_WAIT_L(n) asm volatile("s_waitcnt lgkmcnt(" #n ")" ::: "memory")
; #define PG8_BAR __builtin_amdgcn_s_barrier()
; #define PG8_SCHED __builtin_amdgcn_sched_barrier(0)
; template <class Epi, class Sched, bool ALIGN_EPI = false, bool SP2 = false>
; __device__ __forceinline__ void gemm_phase(PG8_LAS unsigned char* lds, const Gemm g, const Sched& S, const Epi& E, const int tid) {
;     ...
;         const bool has_next = S.next(ui + 1, nxt);
;         const char* nA = has_next ? (const char*)g.A + (size_t)nxt.pm * tstep : cA; const char* nB = has_next ? (const char*)g.Bt + (size_t)nxt.pn * tstep : cB;
;         for (int t = 0; t < nt; t += 2) {
;             const bool last = (t == nt - 2);
;             const char* a1 = cA + (size_t)(t + 1) * kstep;
;             const char* a2 = last ? nA : cA + (size_t)(t + 2) * kstep; const char* b2 = last ? nB : cB + (size_t)(t + 2) * kstep;
;             const char* a3 = a2 + kstep; const char* b3 = b2 + kstep;
;             if (last && has_next) S.a_ready(nxt);
;             if constexpr (SP2) {
;             PG8_LDB(B0, 0, 0); PG8_LDB(B1, 0, 1); PG8_SCHED; PG8_LDA(At, 0, 0); PG8_STAGE(PG8_SA(1, 1), a1 + hstep, voffA);
;             PG8_WAIT_V(8); PG8_WAIT_L(0); PG8_BAR; PG8_MMA(0, 0, At, B0); PG8_MMA(0, 1, At, B1); PG8_BAR; PG8_SCHED;
;             PG8_LDA(At, 0, 1); PG8_STAGE(PG8_SB(0, 0), b2, voffB); PG8_STAGE(PG8_SB(0, 1), b2 + hstep, voffB); PG8_STAGE(PG8_SA(0, 0), a2, voffA);
;             PG8_WAIT_V(8); PG8_WAIT_L(0); PG8_BAR; PG8_MMA(1, 0, At, B0); PG8_MMA(1, 1, At, B1); PG8_BAR; PG8_SCHED;
.LBB0_292:
	s_ashr_i32 s17, s16, 31
	s_lshl_b64 s[18:19], s[16:17], 19
	s_add_u32 s18, s34, s18
	s_addc_u32 s19, s40, s19
	s_and_b64 s[20:21], s[4:5], exec
	s_cselect_b32 s17, s19, s3
	s_cselect_b32 s23, s18, s2
	s_ashr_i32 s15, s14, 31
	s_lshl_b64 s[20:21], s[14:15], 19
	s_add_u32 s20, s41, s20
	s_addc_u32 s21, s42, s21
	s_and_b64 s[36:37], s[4:5], exec
	s_cselect_b32 s15, s21, s27
	s_cselect_b32 s51, s20, s26
	s_add_u32 s2, s2, 0x40080
	s_addc_u32 s3, s3, 0
	s_add_u32 s52, s26, 0x100
	v_mov_b32_e32 v12, 0
	s_addc_u32 s53, s27, 0
	s_mov_b32 s54, -2
	s_add_u32 s26, s2, 0xfffc0080
	s_addc_u32 s27, s3, -1
	s_add_i32 s55, 0, 0x10000
	s_cmp_eq_u32 s54, 12
	s_cselect_b32 s37, s17, s27
	s_cselect_b32 s36, s23, s26
	v_add_u32_e32 v146, s55, v165
	s_cselect_b32 s27, s15, s53
	s_cselect_b32 s26, s51, s52
	s_add_i32 s58, 0, 0x14000
	ds_read_b128 v[166:169], v146
	ds_read_b128 v[172:175], v146 offset:1024
	ds_read_b128 v[176:179], v146 offset:2048
	ds_read_b128 v[180:183], v146 offset:3072
	v_add_u32_e32 v146, s58, v165
	ds_read_b128 v[184:187], v146
	ds_read_b128 v[188:191], v146 offset:1024
	ds_read_b128 v[192:195], v146 offset:2048
	ds_read_b128 v[196:199], v146 offset:3072
	v_lshl_add_u64 v[146:147], s[2:3], 0, v[142:143]
	s_add_i32 m0, s25, 0xc000
	ds_read_b128 v[200:203], v171
	ds_read_b128 v[204:207], v171 offset:1024
	ds_read_b128 v[208:211], v171 offset:2048
	ds_read_b128 v[212:215], v171 offset:3072
	ds_read_b128 v[216:219], v171 offset:4096
	ds_read_b128 v[220:223], v171 offset:5120
	ds_read_b128 v[224:227], v171 offset:6144
	ds_read_b128 v[238:241], v171 offset:7168
	global_load_lds_dwordx4 v[146:147], off
	v_lshl_add_u64 v[146:147], s[2:3], 0, v[144:145]
	s_add_i32 m0, s25, 0xe000
	s_nop 0
	global_load_lds_dwordx4 v[146:147], off
	s_waitcnt vmcnt(8)
	s_waitcnt lgkmcnt(0)
	s_barrier
	s_waitcnt lgkmcnt(0)
	v_mfma_f32_16x16x32_bf16 v[72:75], v[166:169], v[200:203], 0
	v_mfma_f32_16x16x32_bf16 v[68:71], v[176:179], v[200:203], 0
	v_mfma_f32_16x16x32_bf16 v[64:67], v[166:169], v[208:211], 0
	v_mfma_f32_16x16x32_bf16 v[60:63], v[176:179], v[208:211], 0
	v_mfma_f32_16x16x32_bf16 v[56:59], v[166:169], v[216:219], 0
	v_mfma_f32_16x16x32_bf16 v[52:55], v[176:179], v[216:219], 0
	v_mfma_f32_16x16x32_bf16 v[48:51], v[166:169], v[224:227], 0
	v_mfma_f32_16x16x32_bf16 v[44:47], v[176:179], v[224:227], 0
	v_mfma_f32_16x16x32_bf16 v[72:75], v[172:175], v[204:207], v[72:75]
	v_mfma_f32_16x16x32_bf16 v[68:71], v[180:183], v[204:207], v[68:71]
	v_mfma_f32_16x16x32_bf16 v[64:67], v[172:175], v[212:215], v[64:67]
	v_mfma_f32_16x16x32_bf16 v[60:63], v[180:183], v[212:215], v[60:63]
	v_mfma_f32_16x16x32_bf16 v[56:59], v[172:175], v[220:223], v[56:59]
	v_mfma_f32_16x16x32_bf16 v[52:55], v[180:183], v[220:223], v[52:55]
	v_mfma_f32_16x16x32_bf16 v[48:51], v[172:175], v[238:241], v[48:51]
	v_mfma_f32_16x16x32_bf16 v[44:47], v[180:183], v[238:241], v[44:47]
	v_mfma_f32_16x16x32_bf16 v[128:131], v[184:187], v[200:203], 0
	v_mfma_f32_16x16x32_bf16 v[124:127], v[192:195], v[200:203], 0
	v_mfma_f32_16x16x32_bf16 v[120:123], v[184:187], v[208:211], 0
	v_mfma_f32_16x16x32_bf16 v[116:119], v[192:195], v[208:211], 0
	v_mfma_f32_16x16x32_bf16 v[112:115], v[184:187], v[216:219], 0
	v_mfma_f32_16x16x32_bf16 v[108:111], v[192:195], v[216:219], 0
	v_mfma_f32_16x16x32_bf16 v[104:107], v[184:187], v[224:227], 0
	v_mfma_f32_16x16x32_bf16 v[100:103], v[192:195], v[224:227], 0
	v_mfma_f32_16x16x32_bf16 v[128:131], v[188:191], v[204:207], v[128:131]
	v_mfma_f32_16x16x32_bf16 v[124:127], v[196:199], v[204:207], v[124:127]
	v_mfma_f32_16x16x32_bf16 v[120:123], v[188:191], v[212:215], v[120:123]
	v_mfma_f32_16x16x32_bf16 v[116:119], v[196:199], v[212:215], v[116:119]
	v_mfma_f32_16x16x32_bf16 v[112:115], v[188:191], v[220:223], v[112:115]
	v_mfma_f32_16x16x32_bf16 v[108:111], v[196:199], v[220:223], v[108:111]
	v_mfma_f32_16x16x32_bf16 v[104:107], v[188:191], v[238:241], v[104:107]
	v_mfma_f32_16x16x32_bf16 v[100:103], v[196:199], v[238:241], v[100:103]
	s_barrier
	s_add_i32 s55, s55, s43
	v_lshl_add_u64 v[146:147], s[26:27], 0, v[132:133]
	s_mov_b32 m0, s55
	ds_read_b128 v[200:203], v171 offset:16384
	ds_read_b128 v[204:207], v171 offset:17408
	ds_read_b128 v[208:211], v171 offset:18432
	ds_read_b128 v[212:215], v171 offset:19456
	ds_read_b128 v[216:219], v171 offset:20480
	ds_read_b128 v[220:223], v171 offset:21504
	ds_read_b128 v[224:227], v171 offset:22528
	ds_read_b128 v[238:241], v171 offset:23552
	global_load_lds_dwordx4 v[146:147], off
	s_add_i32 m0, s55, 0x2000
	s_add_u32 s56, s26, 0x40000
	v_lshl_add_u64 v[148:149], s[26:27], 0, v[136:137]
	s_addc_u32 s57, s27, 0
	s_add_i32 s55, s58, s43
	global_load_lds_dwordx4 v[148:149], off
	v_lshl_add_u64 v[150:151], s[56:57], 0, v[132:133]
	s_mov_b32 m0, s55
	v_lshl_add_u64 v[242:243], s[36:37], 0, v[134:135]
	global_load_lds_dwordx4 v[150:151], off
	v_lshl_add_u64 v[150:151], s[56:57], 0, v[136:137]
	s_add_i32 m0, s55, 0x2000
	s_nop 0
	global_load_lds_dwordx4 v[150:151], off
	v_lshl_add_u64 v[150:151], s[36:37], 0, v[0:1]
	s_mov_b32 m0, s25
	s_nop 0
	global_load_lds_dwordx4 v[150:151], off
	s_mov_b32 m0, s44
	s_nop 0
	global_load_lds_dwordx4 v[242:243], off
	s_waitcnt vmcnt(8)
	s_waitcnt lgkmcnt(0)
	s_barrier
; #define PG8_STAGE(bufoff, gbase, voff) do { _Pragma("unroll") for (int _i = 0; _i < 2; ++_i) \
;         __builtin_amdgcn_global_load_lds((const unsigned*)((const char*)(gbase) + (voff)[_i]), (PG8_LAS unsigned*)(lds + (bufoff) + ldsw + _i * 8192), 16, 0, 0); } while (0)
; #define PG8_LDA(dst, b, h) do { _Pragma("unroll") for (int m = 0; m < 4; ++m) _Pragma("unroll") for (int k = 0; k < 2; ++k) dst[m][k] = *(const PG8_LAS bf16x8*)(lds + PG8_SA(b, h) + aoff + m * 2048 + k * 1024); } while (0)
; #define PG8_LDB(dst, b, h) do { _Pragma("unroll") for (int n = 0; n < 2; ++n) _Pragma("unroll") for (int k = 0; k < 2; ++k) dst[n][k] = *(const PG8_LAS bf16x8*)(lds + PG8_SB(b, h) + boff + n * 2048 + k * 1024); } while (0)
; #define PG8_MMA(ai, bj, At, Bt) do { __builtin_amdgcn_s_setprio(1); _Pragma("unroll") for (int m = 0; m < 4; ++m) _Pragma("unroll") for (int n = 0; n < 2; ++n) _Pragma("unroll") for (int k = 0; k < 2; ++k) \
;         acc[ai][bj][m][n] = __builtin_amdgcn_mfma_f32_16x16x32_bf16(Bt[n][k], At[m][k], acc[ai][bj][m][n], 0, 0, 0); __builtin_amdgcn_s_setprio(0); } while (0)
; #define PG8_WAIT_V(n) asm volatile("s_waitcnt vmcnt(" #n ")" ::: "memory")
; #define PG8_WAIT_L(n) asm volatile("s_waitcnt lgkmcnt(" #n ")" ::: "memory")
; #define PG8_BAR __builtin_amdgcn_s_barrier()
; #define PG8_SCHED __builtin_amdgcn_sched_barrier(0)
; template <class Epi, class Sched, bool ALIGN_EPI = false, bool SP2 = false>
; __device__ __forceinline__ void gemm_phase(PG8_LAS unsigned char* lds, const Gemm g, const Sched& S, const Epi& E, const int tid) {
;     ...
;             PG8_WAIT_V(8); PG8_WAIT_L(0); PG8_BAR; PG8_MMA(1, 0, At, B0); PG8_MMA(1, 1, At, B1); PG8_BAR; PG8_SCHED;
;             PG8_LDB(B0, 1, 0); PG8_LDB(B1, 1, 1); PG8_SCHED; PG8_LDA(At, 1, 0); PG8_STAGE(PG8_SA(0, 1), a2 + hstep, voffA);
;             PG8_WAIT_V(8); PG8_WAIT_L(0); PG8_BAR; PG8_MMA(0, 0, At, B0); PG8_MMA(0, 1, At, B1); PG8_BAR; PG8_SCHED;
;             PG8_LDA(At, 1, 1); PG8_STAGE(PG8_SB(1, 0), b3, voffB); PG8_STAGE(PG8_SB(1, 1), b3 + hstep, voffB); PG8_STAGE(PG8_SA(1, 0), a3, voffA);
	s_waitcnt lgkmcnt(0)
	v_mfma_f32_16x16x32_bf16 v[40:43], v[166:169], v[200:203], 0
	v_mfma_f32_16x16x32_bf16 v[36:39], v[176:179], v[200:203], 0
	v_mfma_f32_16x16x32_bf16 v[32:35], v[166:169], v[208:211], 0
	v_mfma_f32_16x16x32_bf16 v[28:31], v[176:179], v[208:211], 0
	v_mfma_f32_16x16x32_bf16 v[24:27], v[166:169], v[216:219], 0
	v_mfma_f32_16x16x32_bf16 v[20:23], v[176:179], v[216:219], 0
	v_mfma_f32_16x16x32_bf16 v[8:11], v[166:169], v[224:227], 0
	v_mfma_f32_16x16x32_bf16 v[4:7], v[176:179], v[224:227], 0
	v_mfma_f32_16x16x32_bf16 v[40:43], v[172:175], v[204:207], v[40:43]
	v_mfma_f32_16x16x32_bf16 v[36:39], v[180:183], v[204:207], v[36:39]
	v_mfma_f32_16x16x32_bf16 v[32:35], v[172:175], v[212:215], v[32:35]
	v_mfma_f32_16x16x32_bf16 v[28:31], v[180:183], v[212:215], v[28:31]
	v_mfma_f32_16x16x32_bf16 v[24:27], v[172:175], v[220:223], v[24:27]
	v_mfma_f32_16x16x32_bf16 v[20:23], v[180:183], v[220:223], v[20:23]
	v_mfma_f32_16x16x32_bf16 v[8:11], v[172:175], v[238:241], v[8:11]
	v_mfma_f32_16x16x32_bf16 v[4:7], v[180:183], v[238:241], v[4:7]
	v_mfma_f32_16x16x32_bf16 v[96:99], v[184:187], v[200:203], 0
	v_mfma_f32_16x16x32_bf16 v[92:95], v[192:195], v[200:203], 0
	v_mfma_f32_16x16x32_bf16 v[88:91], v[184:187], v[208:211], 0
	v_mfma_f32_16x16x32_bf16 v[84:87], v[192:195], v[208:211], 0
	v_mfma_f32_16x16x32_bf16 v[80:83], v[184:187], v[216:219], 0
	v_mfma_f32_16x16x32_bf16 v[76:79], v[192:195], v[216:219], 0
	v_mfma_f32_16x16x32_bf16 v[16:19], v[184:187], v[224:227], 0
	v_mfma_f32_16x16x32_bf16 v[12:15], v[192:195], v[224:227], 0
	v_mfma_f32_16x16x32_bf16 v[96:99], v[188:191], v[204:207], v[96:99]
	v_mfma_f32_16x16x32_bf16 v[92:95], v[196:199], v[204:207], v[92:95]
	v_mfma_f32_16x16x32_bf16 v[88:91], v[188:191], v[212:215], v[88:91]
	v_mfma_f32_16x16x32_bf16 v[84:87], v[196:199], v[212:215], v[84:87]
	v_mfma_f32_16x16x32_bf16 v[80:83], v[188:191], v[220:223], v[80:83]
	v_mfma_f32_16x16x32_bf16 v[76:79], v[196:199], v[220:223], v[76:79]
	v_mfma_f32_16x16x32_bf16 v[16:19], v[188:191], v[238:241], v[16:19]
	v_mfma_f32_16x16x32_bf16 v[12:15], v[196:199], v[238:241], v[12:15]
	s_barrier
	s_add_i32 s55, 0, 0x18000
	v_add_u32_e32 v153, s55, v165
	s_add_i32 s56, 0, 0x1c000
	ds_read_b128 v[166:169], v153
	ds_read_b128 v[172:175], v153 offset:1024
	ds_read_b128 v[176:179], v153 offset:2048
	ds_read_b128 v[180:183], v153 offset:3072
	v_add_u32_e32 v153, s56, v165
	ds_read_b128 v[184:187], v153
	ds_read_b128 v[188:191], v153 offset:1024
	ds_read_b128 v[192:195], v153 offset:2048
	ds_read_b128 v[196:199], v153 offset:3072
	s_add_u32 s36, s36, 0x40000
	s_addc_u32 s37, s37, 0
	s_mov_b32 m0, s45
	v_lshl_add_u64 v[244:245], s[36:37], 0, v[0:1]
	ds_read_b128 v[200:203], v171 offset:32768
	ds_read_b128 v[204:207], v171 offset:33792
	ds_read_b128 v[208:211], v171 offset:34816
	ds_read_b128 v[212:215], v171 offset:35840
	ds_read_b128 v[216:219], v171 offset:36864
	ds_read_b128 v[220:223], v171 offset:37888
	ds_read_b128 v[224:227], v171 offset:38912
	ds_read_b128 v[238:241], v171 offset:39936
	global_load_lds_dwordx4 v[244:245], off
	v_lshl_add_u64 v[244:245], s[36:37], 0, v[134:135]
	s_mov_b32 m0, s46
	s_nop 0
	global_load_lds_dwordx4 v[244:245], off
	s_waitcnt vmcnt(8)
	s_waitcnt lgkmcnt(0)
	s_barrier
	s_waitcnt lgkmcnt(0)
	v_mfma_f32_16x16x32_bf16 v[72:75], v[166:169], v[200:203], v[72:75]
	v_mfma_f32_16x16x32_bf16 v[68:71], v[176:179], v[200:203], v[68:71]
	v_mfma_f32_16x16x32_bf16 v[64:67], v[166:169], v[208:211], v[64:67]
	v_mfma_f32_16x16x32_bf16 v[60:63], v[176:179], v[208:211], v[60:63]
	v_mfma_f32_16x16x32_bf16 v[56:59], v[166:169], v[216:219], v[56:59]
	v_mfma_f32_16x16x32_bf16 v[52:55], v[176:179], v[216:219], v[52:55]
	v_mfma_f32_16x16x32_bf16 v[48:51], v[166:169], v[224:227], v[48:51]
	v_mfma_f32_16x16x32_bf16 v[44:47], v[176:179], v[224:227], v[44:47]
	v_mfma_f32_16x16x32_bf16 v[72:75], v[172:175], v[204:207], v[72:75]
	v_mfma_f32_16x16x32_bf16 v[68:71], v[180:183], v[204:207], v[68:71]
	v_mfma_f32_16x16x32_bf16 v[64:67], v[172:175], v[212:215], v[64:67]
	v_mfma_f32_16x16x32_bf16 v[60:63], v[180:183], v[212:215], v[60:63]
	v_mfma_f32_16x16x32_bf16 v[56:59], v[172:175], v[220:223], v[56:59]
	v_mfma_f32_16x16x32_bf16 v[52:55], v[180:183], v[220:223], v[52:55]
	v_mfma_f32_16x16x32_bf16 v[48:51], v[172:175], v[238:241], v[48:51]
	v_mfma_f32_16x16x32_bf16 v[44:47], v[180:183], v[238:241], v[44:47]
	v_mfma_f32_16x16x32_bf16 v[128:131], v[184:187], v[200:203], v[128:131]
	v_mfma_f32_16x16x32_bf16 v[124:127], v[192:195], v[200:203], v[124:127]
	v_mfma_f32_16x16x32_bf16 v[120:123], v[184:187], v[208:211], v[120:123]
	v_mfma_f32_16x16x32_bf16 v[116:119], v[192:195], v[208:211], v[116:119]
	v_mfma_f32_16x16x32_bf16 v[112:115], v[184:187], v[216:219], v[112:115]
	v_mfma_f32_16x16x32_bf16 v[108:111], v[192:195], v[216:219], v[108:111]
	v_mfma_f32_16x16x32_bf16 v[104:107], v[184:187], v[224:227], v[104:107]
	v_mfma_f32_16x16x32_bf16 v[100:103], v[192:195], v[224:227], v[100:103]
	v_mfma_f32_16x16x32_bf16 v[128:131], v[188:191], v[204:207], v[128:131]
	v_mfma_f32_16x16x32_bf16 v[124:127], v[196:199], v[204:207], v[124:127]
	v_mfma_f32_16x16x32_bf16 v[120:123], v[188:191], v[212:215], v[120:123]
	v_mfma_f32_16x16x32_bf16 v[116:119], v[196:199], v[212:215], v[116:119]
	v_mfma_f32_16x16x32_bf16 v[112:115], v[188:191], v[220:223], v[112:115]
	v_mfma_f32_16x16x32_bf16 v[108:111], v[196:199], v[220:223], v[108:111]
	v_mfma_f32_16x16x32_bf16 v[104:107], v[188:191], v[238:241], v[104:107]
	v_mfma_f32_16x16x32_bf16 v[100:103], v[196:199], v[238:241], v[100:103]
	s_barrier
; #define PG8_STAGE(bufoff, gbase, voff) do { _Pragma("unroll") for (int _i = 0; _i < 2; ++_i) \
;         __builtin_amdgcn_global_load_lds((const unsigned*)((const char*)(gbase) + (voff)[_i]), (PG8_LAS unsigned*)(lds + (bufoff) + ldsw + _i * 8192), 16, 0, 0); } while (0)
; #define PG8_LDA(dst, b, h) do { _Pragma("unroll") for (int m = 0; m < 4; ++m) _Pragma("unroll") for (int k = 0; k < 2; ++k) dst[m][k] = *(const PG8_LAS bf16x8*)(lds + PG8_SA(b, h) + aoff + m * 2048 + k * 1024); } while (0)
; #define PG8_MMA(ai, bj, At, Bt) do { __builtin_amdgcn_s_setprio(1); _Pragma("unroll") for (int m = 0; m < 4; ++m) _Pragma("unroll") for (int n = 0; n < 2; ++n) _Pragma("unroll") for (int k = 0; k < 2; ++k) \
;         acc[ai][bj][m][n] = __builtin_amdgcn_mfma_f32_16x16x32_bf16(Bt[n][k], At[m][k], acc[ai][bj][m][n], 0, 0, 0); __builtin_amdgcn_s_setprio(0); } while (0)
; #define PG8_WAIT_V(n) asm volatile("s_waitcnt vmcnt(" #n ")" ::: "memory")
; #define PG8_WAIT_L(n) asm volatile("s_waitcnt lgkmcnt(" #n ")" ::: "memory")
; #define PG8_BAR __builtin_amdgcn_s_barrier()
; #define PG8_SCHED __builtin_amdgcn_sched_barrier(0)
; template <class Epi, class Sched, bool ALIGN_EPI = false, bool SP2 = false>
; __device__ __forceinline__ void gemm_phase(PG8_LAS unsigned char* lds, const Gemm g, const Sched& S, const Epi& E, const int tid) {
;     ...
;             PG8_LDA(At, 1, 1); PG8_STAGE(PG8_SB(1, 0), b3, voffB); PG8_STAGE(PG8_SB(1, 1), b3 + hstep, voffB); PG8_STAGE(PG8_SA(1, 0), a3, voffA);
;             PG8_WAIT_V(8); PG8_WAIT_L(0); PG8_BAR; PG8_MMA(1, 0, At, B0); PG8_MMA(1, 1, At, B1); PG8_BAR; PG8_SCHED;
	s_add_i32 s36, s55, s43
	v_lshl_add_u64 v[146:147], v[146:147], 0, s[0:1]
	s_mov_b32 m0, s36
	ds_read_b128 v[200:203], v171 offset:49152
	ds_read_b128 v[204:207], v171 offset:50176
	ds_read_b128 v[208:211], v171 offset:51200
	ds_read_b128 v[212:215], v171 offset:52224
	ds_read_b128 v[216:219], v171 offset:53248
	ds_read_b128 v[220:223], v171 offset:54272
	ds_read_b128 v[224:227], v171 offset:55296
	ds_read_b128 v[238:241], v171 offset:56320
	global_load_lds_dwordx4 v[146:147], off
	s_add_i32 m0, s36, 0x2000
	s_add_u32 s26, s26, 0x40080
	v_lshl_add_u64 v[146:147], v[148:149], 0, s[0:1]
	s_addc_u32 s27, s27, 0
	s_add_i32 s36, s56, s43
	global_load_lds_dwordx4 v[146:147], off
	v_lshl_add_u64 v[146:147], s[26:27], 0, v[132:133]
	s_mov_b32 m0, s36
	s_nop 0
	global_load_lds_dwordx4 v[146:147], off
	v_lshl_add_u64 v[146:147], s[26:27], 0, v[136:137]
	s_add_i32 m0, s36, 0x2000
	s_nop 0
	global_load_lds_dwordx4 v[146:147], off
	v_lshl_add_u64 v[146:147], v[150:151], 0, s[0:1]
	s_mov_b32 m0, s48
	s_nop 0
	global_load_lds_dwordx4 v[146:147], off
	v_lshl_add_u64 v[146:147], v[242:243], 0, s[0:1]
	s_mov_b32 m0, s49
	s_nop 0
	global_load_lds_dwordx4 v[146:147], off
	s_waitcnt vmcnt(8)
	s_waitcnt lgkmcnt(0)
	s_barrier
	s_waitcnt lgkmcnt(0)
	v_mfma_f32_16x16x32_bf16 v[40:43], v[166:169], v[200:203], v[40:43]
	v_mfma_f32_16x16x32_bf16 v[36:39], v[176:179], v[200:203], v[36:39]
	v_mfma_f32_16x16x32_bf16 v[32:35], v[166:169], v[208:211], v[32:35]
	v_mfma_f32_16x16x32_bf16 v[28:31], v[176:179], v[208:211], v[28:31]
	v_mfma_f32_16x16x32_bf16 v[24:27], v[166:169], v[216:219], v[24:27]
	v_mfma_f32_16x16x32_bf16 v[20:23], v[176:179], v[216:219], v[20:23]
	v_mfma_f32_16x16x32_bf16 v[8:11], v[166:169], v[224:227], v[8:11]
	v_mfma_f32_16x16x32_bf16 v[4:7], v[176:179], v[224:227], v[4:7]
	v_mfma_f32_16x16x32_bf16 v[40:43], v[172:175], v[204:207], v[40:43]
	v_mfma_f32_16x16x32_bf16 v[36:39], v[180:183], v[204:207], v[36:39]
	v_mfma_f32_16x16x32_bf16 v[32:35], v[172:175], v[212:215], v[32:35]
	v_mfma_f32_16x16x32_bf16 v[28:31], v[180:183], v[212:215], v[28:31]
	v_mfma_f32_16x16x32_bf16 v[24:27], v[172:175], v[220:223], v[24:27]
	v_mfma_f32_16x16x32_bf16 v[20:23], v[180:183], v[220:223], v[20:23]
	v_mfma_f32_16x16x32_bf16 v[8:11], v[172:175], v[238:241], v[8:11]
	v_mfma_f32_16x16x32_bf16 v[4:7], v[180:183], v[238:241], v[4:7]
	v_mfma_f32_16x16x32_bf16 v[96:99], v[184:187], v[200:203], v[96:99]
	v_mfma_f32_16x16x32_bf16 v[92:95], v[192:195], v[200:203], v[92:95]
	v_mfma_f32_16x16x32_bf16 v[88:91], v[184:187], v[208:211], v[88:91]
	v_mfma_f32_16x16x32_bf16 v[84:87], v[192:195], v[208:211], v[84:87]
	v_mfma_f32_16x16x32_bf16 v[80:83], v[184:187], v[216:219], v[80:83]
	v_mfma_f32_16x16x32_bf16 v[76:79], v[192:195], v[216:219], v[76:79]
	v_mfma_f32_16x16x32_bf16 v[16:19], v[184:187], v[224:227], v[16:19]
	v_mfma_f32_16x16x32_bf16 v[12:15], v[192:195], v[224:227], v[12:15]
	v_mfma_f32_16x16x32_bf16 v[96:99], v[188:191], v[204:207], v[96:99]
	v_mfma_f32_16x16x32_bf16 v[92:95], v[196:199], v[204:207], v[92:95]
	v_mfma_f32_16x16x32_bf16 v[88:91], v[188:191], v[212:215], v[88:91]
	v_mfma_f32_16x16x32_bf16 v[84:87], v[196:199], v[212:215], v[84:87]
	v_mfma_f32_16x16x32_bf16 v[80:83], v[188:191], v[220:223], v[80:83]
	v_mfma_f32_16x16x32_bf16 v[76:79], v[196:199], v[220:223], v[76:79]
	v_mfma_f32_16x16x32_bf16 v[16:19], v[188:191], v[238:241], v[16:19]
	v_mfma_f32_16x16x32_bf16 v[12:15], v[196:199], v[238:241], v[12:15]
	s_barrier
	s_add_i32 s54, s54, 2
	s_add_u32 s2, s2, 0x100
	s_addc_u32 s3, s3, 0
	s_add_u32 s52, s52, 0x100
	s_addc_u32 s53, s53, 0
	s_cmp_gt_u32 s54, 13
	s_cbranch_scc0 .LBB0_293
	s_branch .Lpeel_exit1

; #define PG8_BAR __builtin_amdgcn_s_barrier()
; template <class Epi, class Sched, bool ALIGN_EPI = false, bool SP2 = false>
; __device__ __forceinline__ void gemm_phase(PG8_LAS unsigned char* lds, const Gemm g, const Sched& S, const Epi& E, const int tid) {
;     ...
;         if constexpr (ALIGN_EPI) { if (wr == 0) PG8_BAR; }
.Lpeel_exit1:
	s_and_b64 vcc, exec, s[10:11]
	s_cbranch_vccz .LBB0_296
	s_barrier

; #define PG8_STAGE(bufoff, gbase, voff) do { _Pragma("unroll") for (int _i = 0; _i < 2; ++_i) \
;         __builtin_amdgcn_global_load_lds((const unsigned*)((const char*)(gbase) + (voff)[_i]), (PG8_LAS unsigned*)(lds + (bufoff) + ldsw + _i * 8192), 16, 0, 0); } while (0)
; #define PG8_LDA(dst, b, h) do { _Pragma("unroll") for (int m = 0; m < 4; ++m) _Pragma("unroll") for (int k = 0; k < 2; ++k) dst[m][k] = *(const PG8_LAS bf16x8*)(lds + PG8_SA(b, h) + aoff + m * 2048 + k * 1024); } while (0)
; #define PG8_LDB(dst, b, h) do { _Pragma("unroll") for (int n = 0; n < 2; ++n) _Pragma("unroll") for (int k = 0; k < 2; ++k) dst[n][k] = *(const PG8_LAS bf16x8*)(lds + PG8_SB(b, h) + boff + n * 2048 + k * 1024); } while (0)
; #define PG8_WAIT_V(n) asm volatile("s_waitcnt vmcnt(" #n ")" ::: "memory")
; #define PG8_WAIT_L(n) asm volatile("s_waitcnt lgkmcnt(" #n ")" ::: "memory")
; #define PG8_BAR __builtin_amdgcn_s_barrier()
; #define PG8_SCHED __builtin_amdgcn_sched_barrier(0)
; template <class Epi, class Sched, bool ALIGN_EPI = false, bool SP2 = false>
; __device__ __forceinline__ void gemm_phase(PG8_LAS unsigned char* lds, const Gemm g, const Sched& S, const Epi& E, const int tid) {
;     ...
;         const bool has_next = S.next(ui + 1, nxt);
;         const char* nA = has_next ? (const char*)g.A + (size_t)nxt.pm * tstep : cA; const char* nB = has_next ? (const char*)g.Bt + (size_t)nxt.pn * tstep : cB;
;         for (int t = 0; t < nt; t += 2) {
;             const bool last = (t == nt - 2);
;             const char* a1 = cA + (size_t)(t + 1) * kstep;
;             const char* a2 = last ? nA : cA + (size_t)(t + 2) * kstep; const char* b2 = last ? nB : cB + (size_t)(t + 2) * kstep;
;             const char* a3 = a2 + kstep; const char* b3 = b2 + kstep;
;             if (last && has_next) S.a_ready(nxt);
;             if constexpr (SP2) {
;             PG8_LDB(B0, 0, 0); PG8_LDB(B1, 0, 1); PG8_SCHED; PG8_LDA(At, 0, 0); PG8_STAGE(PG8_SA(1, 1), a1 + hstep, voffA);
;             PG8_WAIT_V(8); PG8_WAIT_L(0); PG8_BAR; PG8_MMA(0, 0, At, B0); PG8_MMA(0, 1, At, B1); PG8_BAR; PG8_SCHED;
;             PG8_LDA(At, 0, 1); PG8_STAGE(PG8_SB(0, 0), b2, voffB); PG8_STAGE(PG8_SB(0, 1), b2 + hstep, voffB); PG8_STAGE(PG8_SA(0, 0), a2, voffA);
;             PG8_WAIT_V(8); PG8_WAIT_L(0); PG8_BAR; PG8_MMA(1, 0, At, B0); PG8_MMA(1, 1, At, B1); PG8_BAR; PG8_SCHED;
.LBB0_475:
	s_add_u32 s6, s6, 0x80
	s_addc_u32 s7, s7, 0
	s_add_u32 s78, s58, 0x100
	v_mov_b32_e32 v4, 0
	s_addc_u32 s79, s59, 0
	s_mov_b32 s58, 0
	s_add_i32 s80, s58, 2
	s_add_u32 s81, s6, 0x80
	s_addc_u32 s59, s7, 0
	s_add_i32 s87, 0, 0x10000
	s_cmp_eq_u32 s70, s58
	s_cselect_b32 s59, s55, s59
	s_cselect_b32 s58, s54, s81
	v_add_u32_e32 v144, s87, v184
	s_cselect_b32 s83, s57, s79
	s_cselect_b32 s82, s56, s78
	s_add_i32 s81, 0, 0x14000
	ds_read_b128 v[132:135], v144
	ds_read_b128 v[136:139], v144 offset:1024
	ds_read_b128 v[140:143], v144 offset:2048
	ds_read_b128 v[174:177], v144 offset:3072
	v_add_u32_e32 v144, s81, v184
	ds_read_b128 v[178:181], v144
	ds_read_b128 v[188:191], v144 offset:1024
	ds_read_b128 v[192:195], v144 offset:2048
	ds_read_b128 v[196:199], v144 offset:3072
	v_lshl_add_u64 v[144:145], s[6:7], 0, v[170:171]
	s_add_i32 m0, s62, 0xc000
	ds_read_b128 v[200:203], v186
	ds_read_b128 v[204:207], v186 offset:1024
	ds_read_b128 v[208:211], v186 offset:2048
	ds_read_b128 v[212:215], v186 offset:3072
	ds_read_b128 v[216:219], v186 offset:4096
	ds_read_b128 v[220:223], v186 offset:5120
	ds_read_b128 v[224:227], v186 offset:6144
	ds_read_b128 v[238:241], v186 offset:7168
	global_load_lds_dwordx4 v[144:145], off
	v_lshl_add_u64 v[144:145], s[6:7], 0, v[172:173]
	s_add_i32 m0, s62, 0xe000
	s_nop 0
	global_load_lds_dwordx4 v[144:145], off
	s_waitcnt vmcnt(8)
	s_waitcnt lgkmcnt(0)
	s_barrier
	s_waitcnt lgkmcnt(0)
	v_mfma_f32_16x16x32_bf16 v[128:131], v[132:135], v[200:203], 0
	v_mfma_f32_16x16x32_bf16 v[124:127], v[140:143], v[200:203], 0
	v_mfma_f32_16x16x32_bf16 v[112:115], v[132:135], v[208:211], 0
	v_mfma_f32_16x16x32_bf16 v[108:111], v[140:143], v[208:211], 0
	v_mfma_f32_16x16x32_bf16 v[96:99], v[132:135], v[216:219], 0
	v_mfma_f32_16x16x32_bf16 v[92:95], v[140:143], v[216:219], 0
	v_mfma_f32_16x16x32_bf16 v[80:83], v[132:135], v[224:227], 0
	v_mfma_f32_16x16x32_bf16 v[76:79], v[140:143], v[224:227], 0
	v_mfma_f32_16x16x32_bf16 v[128:131], v[136:139], v[204:207], v[128:131]
	v_mfma_f32_16x16x32_bf16 v[124:127], v[174:177], v[204:207], v[124:127]
	v_mfma_f32_16x16x32_bf16 v[112:115], v[136:139], v[212:215], v[112:115]
	v_mfma_f32_16x16x32_bf16 v[108:111], v[174:177], v[212:215], v[108:111]
	v_mfma_f32_16x16x32_bf16 v[96:99], v[136:139], v[220:223], v[96:99]
	v_mfma_f32_16x16x32_bf16 v[92:95], v[174:177], v[220:223], v[92:95]
	v_mfma_f32_16x16x32_bf16 v[80:83], v[136:139], v[238:241], v[80:83]
	v_mfma_f32_16x16x32_bf16 v[76:79], v[174:177], v[238:241], v[76:79]
	v_mfma_f32_16x16x32_bf16 v[120:123], v[178:181], v[200:203], 0
	v_mfma_f32_16x16x32_bf16 v[116:119], v[192:195], v[200:203], 0
	v_mfma_f32_16x16x32_bf16 v[104:107], v[178:181], v[208:211], 0
	v_mfma_f32_16x16x32_bf16 v[100:103], v[192:195], v[208:211], 0
	v_mfma_f32_16x16x32_bf16 v[88:91], v[178:181], v[216:219], 0
	v_mfma_f32_16x16x32_bf16 v[84:87], v[192:195], v[216:219], 0
	v_mfma_f32_16x16x32_bf16 v[72:75], v[178:181], v[224:227], 0
	v_mfma_f32_16x16x32_bf16 v[68:71], v[192:195], v[224:227], 0
	v_mfma_f32_16x16x32_bf16 v[120:123], v[188:191], v[204:207], v[120:123]
	v_mfma_f32_16x16x32_bf16 v[116:119], v[196:199], v[204:207], v[116:119]
	v_mfma_f32_16x16x32_bf16 v[104:107], v[188:191], v[212:215], v[104:107]
	v_mfma_f32_16x16x32_bf16 v[100:103], v[196:199], v[212:215], v[100:103]
	v_mfma_f32_16x16x32_bf16 v[88:91], v[188:191], v[220:223], v[88:91]
	v_mfma_f32_16x16x32_bf16 v[84:87], v[196:199], v[220:223], v[84:87]
	v_mfma_f32_16x16x32_bf16 v[72:75], v[188:191], v[238:241], v[72:75]
	v_mfma_f32_16x16x32_bf16 v[68:71], v[196:199], v[238:241], v[68:71]
	s_barrier
	s_add_i32 s87, s87, s61
	v_lshl_add_u64 v[144:145], s[82:83], 0, v[146:147]
	s_mov_b32 m0, s87
	ds_read_b128 v[200:203], v186 offset:16384
	ds_read_b128 v[204:207], v186 offset:17408
	ds_read_b128 v[208:211], v186 offset:18432
	ds_read_b128 v[212:215], v186 offset:19456
	ds_read_b128 v[216:219], v186 offset:20480
	ds_read_b128 v[220:223], v186 offset:21504
	ds_read_b128 v[224:227], v186 offset:22528
	ds_read_b128 v[238:241], v186 offset:23552
	global_load_lds_dwordx4 v[144:145], off
	s_add_i32 m0, s87, 0x2000
	v_lshl_add_u64 v[242:243], s[82:83], 0, v[168:169]
	s_add_u32 s82, s82, s14
	s_addc_u32 s83, s83, 0
	s_add_i32 s81, s81, s61
	global_load_lds_dwordx4 v[242:243], off
	v_lshl_add_u64 v[244:245], s[82:83], 0, v[146:147]
	s_mov_b32 m0, s81
	v_lshl_add_u64 v[246:247], s[82:83], 0, v[168:169]
	global_load_lds_dwordx4 v[244:245], off
	s_add_i32 m0, s81, 0x2000
	v_lshl_add_u64 v[248:249], s[58:59], 0, v[0:1]
	global_load_lds_dwordx4 v[246:247], off
	s_mov_b32 m0, s62
	v_lshl_add_u64 v[148:149], s[58:59], 0, v[166:167]
	global_load_lds_dwordx4 v[248:249], off
	s_mov_b32 m0, s63
	s_nop 0
	global_load_lds_dwordx4 v[148:149], off
	s_waitcnt vmcnt(8)
	s_waitcnt lgkmcnt(0)
	s_barrier
; #define PG8_STAGE(bufoff, gbase, voff) do { _Pragma("unroll") for (int _i = 0; _i < 2; ++_i) \
;         __builtin_amdgcn_global_load_lds((const unsigned*)((const char*)(gbase) + (voff)[_i]), (PG8_LAS unsigned*)(lds + (bufoff) + ldsw + _i * 8192), 16, 0, 0); } while (0)
; #define PG8_LDA(dst, b, h) do { _Pragma("unroll") for (int m = 0; m < 4; ++m) _Pragma("unroll") for (int k = 0; k < 2; ++k) dst[m][k] = *(const PG8_LAS bf16x8*)(lds + PG8_SA(b, h) + aoff + m * 2048 + k * 1024); } while (0)
; #define PG8_LDB(dst, b, h) do { _Pragma("unroll") for (int n = 0; n < 2; ++n) _Pragma("unroll") for (int k = 0; k < 2; ++k) dst[n][k] = *(const PG8_LAS bf16x8*)(lds + PG8_SB(b, h) + boff + n * 2048 + k * 1024); } while (0)
; #define PG8_MMA(ai, bj, At, Bt) do { __builtin_amdgcn_s_setprio(1); _Pragma("unroll") for (int m = 0; m < 4; ++m) _Pragma("unroll") for (int n = 0; n < 2; ++n) _Pragma("unroll") for (int k = 0; k < 2; ++k) \
;         acc[ai][bj][m][n] = __builtin_amdgcn_mfma_f32_16x16x32_bf16(Bt[n][k], At[m][k], acc[ai][bj][m][n], 0, 0, 0); __builtin_amdgcn_s_setprio(0); } while (0)
; #define PG8_WAIT_V(n) asm volatile("s_waitcnt vmcnt(" #n ")" ::: "memory")
; #define PG8_WAIT_L(n) asm volatile("s_waitcnt lgkmcnt(" #n ")" ::: "memory")
; #define PG8_BAR __builtin_amdgcn_s_barrier()
; #define PG8_SCHED __builtin_amdgcn_sched_barrier(0)
; template <class Epi, class Sched, bool ALIGN_EPI = false, bool SP2 = false>
; __device__ __forceinline__ void gemm_phase(PG8_LAS unsigned char* lds, const Gemm g, const Sched& S, const Epi& E, const int tid) {
;     ...
;             PG8_WAIT_V(8); PG8_WAIT_L(0); PG8_BAR; PG8_MMA(1, 0, At, B0); PG8_MMA(1, 1, At, B1); PG8_BAR; PG8_SCHED;
;             PG8_LDB(B0, 1, 0); PG8_LDB(B1, 1, 1); PG8_SCHED; PG8_LDA(At, 1, 0); PG8_STAGE(PG8_SA(0, 1), a2 + hstep, voffA);
;             PG8_WAIT_V(8); PG8_WAIT_L(0); PG8_BAR; PG8_MMA(0, 0, At, B0); PG8_MMA(0, 1, At, B1); PG8_BAR; PG8_SCHED;
;             PG8_LDA(At, 1, 1); PG8_STAGE(PG8_SB(1, 0), b3, voffB); PG8_STAGE(PG8_SB(1, 1), b3 + hstep, voffB); PG8_STAGE(PG8_SA(1, 0), a3, voffA);
	s_waitcnt lgkmcnt(0)
	v_mfma_f32_16x16x32_bf16 v[64:67], v[132:135], v[200:203], 0
	v_mfma_f32_16x16x32_bf16 v[60:63], v[140:143], v[200:203], 0
	v_mfma_f32_16x16x32_bf16 v[48:51], v[132:135], v[208:211], 0
	v_mfma_f32_16x16x32_bf16 v[44:47], v[140:143], v[208:211], 0
	v_mfma_f32_16x16x32_bf16 v[32:35], v[132:135], v[216:219], 0
	v_mfma_f32_16x16x32_bf16 v[28:31], v[140:143], v[216:219], 0
	v_mfma_f32_16x16x32_bf16 v[16:19], v[132:135], v[224:227], 0
	v_mfma_f32_16x16x32_bf16 v[12:15], v[140:143], v[224:227], 0
	v_mfma_f32_16x16x32_bf16 v[64:67], v[136:139], v[204:207], v[64:67]
	v_mfma_f32_16x16x32_bf16 v[60:63], v[174:177], v[204:207], v[60:63]
	v_mfma_f32_16x16x32_bf16 v[48:51], v[136:139], v[212:215], v[48:51]
	v_mfma_f32_16x16x32_bf16 v[44:47], v[174:177], v[212:215], v[44:47]
	v_mfma_f32_16x16x32_bf16 v[32:35], v[136:139], v[220:223], v[32:35]
	v_mfma_f32_16x16x32_bf16 v[28:31], v[174:177], v[220:223], v[28:31]
	v_mfma_f32_16x16x32_bf16 v[16:19], v[136:139], v[238:241], v[16:19]
	v_mfma_f32_16x16x32_bf16 v[12:15], v[174:177], v[238:241], v[12:15]
	v_mfma_f32_16x16x32_bf16 v[56:59], v[178:181], v[200:203], 0
	v_mfma_f32_16x16x32_bf16 v[52:55], v[192:195], v[200:203], 0
	v_mfma_f32_16x16x32_bf16 v[40:43], v[178:181], v[208:211], 0
	v_mfma_f32_16x16x32_bf16 v[36:39], v[192:195], v[208:211], 0
	v_mfma_f32_16x16x32_bf16 v[24:27], v[178:181], v[216:219], 0
	v_mfma_f32_16x16x32_bf16 v[20:23], v[192:195], v[216:219], 0
	v_mfma_f32_16x16x32_bf16 v[8:11], v[178:181], v[224:227], 0
	v_mfma_f32_16x16x32_bf16 v[4:7], v[192:195], v[224:227], 0
	v_mfma_f32_16x16x32_bf16 v[56:59], v[188:191], v[204:207], v[56:59]
	v_mfma_f32_16x16x32_bf16 v[52:55], v[196:199], v[204:207], v[52:55]
	v_mfma_f32_16x16x32_bf16 v[40:43], v[188:191], v[212:215], v[40:43]
	v_mfma_f32_16x16x32_bf16 v[36:39], v[196:199], v[212:215], v[36:39]
	v_mfma_f32_16x16x32_bf16 v[24:27], v[188:191], v[220:223], v[24:27]
	v_mfma_f32_16x16x32_bf16 v[20:23], v[196:199], v[220:223], v[20:23]
	v_mfma_f32_16x16x32_bf16 v[8:11], v[188:191], v[238:241], v[8:11]
	v_mfma_f32_16x16x32_bf16 v[4:7], v[196:199], v[238:241], v[4:7]
	s_barrier
	s_add_i32 s81, 0, 0x18000
	v_add_u32_e32 v150, s81, v184
	s_add_i32 s82, 0, 0x1c000
	ds_read_b128 v[132:135], v150
	ds_read_b128 v[136:139], v150 offset:1024
	ds_read_b128 v[140:143], v150 offset:2048
	ds_read_b128 v[174:177], v150 offset:3072
	v_add_u32_e32 v150, s82, v184
	ds_read_b128 v[178:181], v150
	ds_read_b128 v[188:191], v150 offset:1024
	ds_read_b128 v[192:195], v150 offset:2048
	ds_read_b128 v[196:199], v150 offset:3072
	s_add_u32 s58, s58, s14
	s_addc_u32 s59, s59, 0
	s_mov_b32 m0, s64
	v_lshl_add_u64 v[150:151], s[58:59], 0, v[0:1]
	ds_read_b128 v[200:203], v186 offset:32768
	ds_read_b128 v[204:207], v186 offset:33792
	ds_read_b128 v[208:211], v186 offset:34816
	ds_read_b128 v[212:215], v186 offset:35840
	ds_read_b128 v[216:219], v186 offset:36864
	ds_read_b128 v[220:223], v186 offset:37888
	ds_read_b128 v[224:227], v186 offset:38912
	ds_read_b128 v[238:241], v186 offset:39936
	global_load_lds_dwordx4 v[150:151], off
	v_lshl_add_u64 v[150:151], s[58:59], 0, v[166:167]
	s_mov_b32 m0, s65
	s_nop 0
	global_load_lds_dwordx4 v[150:151], off
	s_waitcnt vmcnt(8)
	s_waitcnt lgkmcnt(0)
	s_barrier
	s_waitcnt lgkmcnt(0)
	v_mfma_f32_16x16x32_bf16 v[128:131], v[132:135], v[200:203], v[128:131]
	v_mfma_f32_16x16x32_bf16 v[124:127], v[140:143], v[200:203], v[124:127]
	v_mfma_f32_16x16x32_bf16 v[112:115], v[132:135], v[208:211], v[112:115]
	v_mfma_f32_16x16x32_bf16 v[108:111], v[140:143], v[208:211], v[108:111]
	v_mfma_f32_16x16x32_bf16 v[96:99], v[132:135], v[216:219], v[96:99]
	v_mfma_f32_16x16x32_bf16 v[92:95], v[140:143], v[216:219], v[92:95]
	v_mfma_f32_16x16x32_bf16 v[80:83], v[132:135], v[224:227], v[80:83]
	v_mfma_f32_16x16x32_bf16 v[76:79], v[140:143], v[224:227], v[76:79]
	v_mfma_f32_16x16x32_bf16 v[128:131], v[136:139], v[204:207], v[128:131]
	v_mfma_f32_16x16x32_bf16 v[124:127], v[174:177], v[204:207], v[124:127]
	v_mfma_f32_16x16x32_bf16 v[112:115], v[136:139], v[212:215], v[112:115]
	v_mfma_f32_16x16x32_bf16 v[108:111], v[174:177], v[212:215], v[108:111]
	v_mfma_f32_16x16x32_bf16 v[96:99], v[136:139], v[220:223], v[96:99]
	v_mfma_f32_16x16x32_bf16 v[92:95], v[174:177], v[220:223], v[92:95]
	v_mfma_f32_16x16x32_bf16 v[80:83], v[136:139], v[238:241], v[80:83]
	v_mfma_f32_16x16x32_bf16 v[76:79], v[174:177], v[238:241], v[76:79]
	v_mfma_f32_16x16x32_bf16 v[120:123], v[178:181], v[200:203], v[120:123]
	v_mfma_f32_16x16x32_bf16 v[116:119], v[192:195], v[200:203], v[116:119]
	v_mfma_f32_16x16x32_bf16 v[104:107], v[178:181], v[208:211], v[104:107]
	v_mfma_f32_16x16x32_bf16 v[100:103], v[192:195], v[208:211], v[100:103]
	v_mfma_f32_16x16x32_bf16 v[88:91], v[178:181], v[216:219], v[88:91]
	v_mfma_f32_16x16x32_bf16 v[84:87], v[192:195], v[216:219], v[84:87]
	v_mfma_f32_16x16x32_bf16 v[72:75], v[178:181], v[224:227], v[72:75]
	v_mfma_f32_16x16x32_bf16 v[68:71], v[192:195], v[224:227], v[68:71]
	v_mfma_f32_16x16x32_bf16 v[120:123], v[188:191], v[204:207], v[120:123]
	v_mfma_f32_16x16x32_bf16 v[116:119], v[196:199], v[204:207], v[116:119]
	v_mfma_f32_16x16x32_bf16 v[104:107], v[188:191], v[212:215], v[104:107]
	v_mfma_f32_16x16x32_bf16 v[100:103], v[196:199], v[212:215], v[100:103]
	v_mfma_f32_16x16x32_bf16 v[88:91], v[188:191], v[220:223], v[88:91]
	v_mfma_f32_16x16x32_bf16 v[84:87], v[196:199], v[220:223], v[84:87]
	v_mfma_f32_16x16x32_bf16 v[72:75], v[188:191], v[238:241], v[72:75]
	v_mfma_f32_16x16x32_bf16 v[68:71], v[196:199], v[238:241], v[68:71]
	s_barrier
; #define PG8_STAGE(bufoff, gbase, voff) do { _Pragma("unroll") for (int _i = 0; _i < 2; ++_i) \
;         __builtin_amdgcn_global_load_lds((const unsigned*)((const char*)(gbase) + (voff)[_i]), (PG8_LAS unsigned*)(lds + (bufoff) + ldsw + _i * 8192), 16, 0, 0); } while (0)
; #define PG8_LDA(dst, b, h) do { _Pragma("unroll") for (int m = 0; m < 4; ++m) _Pragma("unroll") for (int k = 0; k < 2; ++k) dst[m][k] = *(const PG8_LAS bf16x8*)(lds + PG8_SA(b, h) + aoff + m * 2048 + k * 1024); } while (0)
; #define PG8_LDB(dst, b, h) do { _Pragma("unroll") for (int n = 0; n < 2; ++n) _Pragma("unroll") for (int k = 0; k < 2; ++k) dst[n][k] = *(const PG8_LAS bf16x8*)(lds + PG8_SB(b, h) + boff + n * 2048 + k * 1024); } while (0)
; #define PG8_MMA(ai, bj, At, Bt) do { __builtin_amdgcn_s_setprio(1); _Pragma("unroll") for (int m = 0; m < 4; ++m) _Pragma("unroll") for (int n = 0; n < 2; ++n) _Pragma("unroll") for (int k = 0; k < 2; ++k) \
;         acc[ai][bj][m][n] = __builtin_amdgcn_mfma_f32_16x16x32_bf16(Bt[n][k], At[m][k], acc[ai][bj][m][n], 0, 0, 0); __builtin_amdgcn_s_setprio(0); } while (0)
; #define PG8_BAR __builtin_amdgcn_s_barrier()
; template <class Epi, class Sched, bool ALIGN_EPI = false, bool SP2 = false>
; __device__ __forceinline__ void gemm_phase(PG8_LAS unsigned char* lds, const Gemm g, const Sched& S, const Epi& E, const int tid) {
;     ...
;             PG8_LDB(B0, 0, 0); PG8_LDB(B1, 0, 1); PG8_SCHED; PG8_LDA(At, 0, 0); PG8_STAGE(PG8_SA(1, 1), a1 + hstep, voffA);
;             PG8_WAIT_V(8); PG8_WAIT_L(0); PG8_BAR; PG8_MMA(0, 0, At, B0); PG8_MMA(0, 1, At, B1); PG8_BAR; PG8_SCHED;
;             PG8_LDA(At, 0, 1); PG8_STAGE(PG8_SB(0, 0), b2, voffB); PG8_STAGE(PG8_SB(0, 1), b2 + hstep, voffB); PG8_STAGE(PG8_SA(0, 0), a2, voffA);
;             PG8_WAIT_V(8); PG8_WAIT_L(0); PG8_BAR; PG8_MMA(1, 0, At, B0); PG8_MMA(1, 1, At, B1); PG8_BAR; PG8_SCHED;
;             PG8_LDB(B0, 1, 0); PG8_LDB(B1, 1, 1); PG8_SCHED; PG8_LDA(At, 1, 0); PG8_STAGE(PG8_SA(0, 1), a2 + hstep, voffA);
;             PG8_WAIT_V(8); PG8_WAIT_L(0); PG8_BAR; PG8_MMA(0, 0, At, B0); PG8_MMA(0, 1, At, B1); PG8_BAR; PG8_SCHED;
;             PG8_LDA(At, 1, 1); PG8_STAGE(PG8_SB(1, 0), b3, voffB); PG8_STAGE(PG8_SB(1, 1), b3 + hstep, voffB); PG8_STAGE(PG8_SA(1, 0), a3, voffA);
;             PG8_WAIT_V(8); PG8_WAIT_L(0); PG8_BAR; PG8_MMA(1, 0, At, B0); PG8_MMA(1, 1, At, B1); PG8_BAR; PG8_SCHED;
	s_add_i32 s58, s81, s61
	v_lshl_add_u64 v[144:145], v[144:145], 0, s[0:1]
	s_mov_b32 m0, s58
	ds_read_b128 v[200:203], v186 offset:49152
	ds_read_b128 v[204:207], v186 offset:50176
	ds_read_b128 v[208:211], v186 offset:51200
	ds_read_b128 v[212:215], v186 offset:52224
	ds_read_b128 v[216:219], v186 offset:53248
	ds_read_b128 v[220:223], v186 offset:54272
	ds_read_b128 v[224:227], v186 offset:55296
	ds_read_b128 v[238:241], v186 offset:56320
	global_load_lds_dwordx4 v[144:145], off
	v_lshl_add_u64 v[144:145], v[242:243], 0, s[0:1]
	s_add_i32 m0, s58, 0x2000
	s_add_i32 s58, s82, s61
	global_load_lds_dwordx4 v[144:145], off
	v_lshl_add_u64 v[144:145], v[244:245], 0, s[0:1]
	s_mov_b32 m0, s58
	s_nop 0
	global_load_lds_dwordx4 v[144:145], off
	v_lshl_add_u64 v[144:145], v[246:247], 0, s[0:1]
	s_add_i32 m0, s58, 0x2000
	s_nop 0
	global_load_lds_dwordx4 v[144:145], off
	v_lshl_add_u64 v[144:145], v[248:249], 0, s[0:1]
	s_mov_b32 m0, s66
	s_nop 0
	global_load_lds_dwordx4 v[144:145], off
	v_lshl_add_u64 v[144:145], v[148:149], 0, s[0:1]
	s_mov_b32 m0, s67
	s_nop 0
	global_load_lds_dwordx4 v[144:145], off
	s_waitcnt vmcnt(8)
	s_waitcnt lgkmcnt(0)
	s_barrier
	s_waitcnt lgkmcnt(0)
	v_mfma_f32_16x16x32_bf16 v[64:67], v[132:135], v[200:203], v[64:67]
	v_mfma_f32_16x16x32_bf16 v[60:63], v[140:143], v[200:203], v[60:63]
	v_mfma_f32_16x16x32_bf16 v[48:51], v[132:135], v[208:211], v[48:51]
	v_mfma_f32_16x16x32_bf16 v[44:47], v[140:143], v[208:211], v[44:47]
	v_mfma_f32_16x16x32_bf16 v[32:35], v[132:135], v[216:219], v[32:35]
	v_mfma_f32_16x16x32_bf16 v[28:31], v[140:143], v[216:219], v[28:31]
	v_mfma_f32_16x16x32_bf16 v[16:19], v[132:135], v[224:227], v[16:19]
	v_mfma_f32_16x16x32_bf16 v[12:15], v[140:143], v[224:227], v[12:15]
	v_mfma_f32_16x16x32_bf16 v[64:67], v[136:139], v[204:207], v[64:67]
	v_mfma_f32_16x16x32_bf16 v[60:63], v[174:177], v[204:207], v[60:63]
	v_mfma_f32_16x16x32_bf16 v[48:51], v[136:139], v[212:215], v[48:51]
	v_mfma_f32_16x16x32_bf16 v[44:47], v[174:177], v[212:215], v[44:47]
	v_mfma_f32_16x16x32_bf16 v[32:35], v[136:139], v[220:223], v[32:35]
	v_mfma_f32_16x16x32_bf16 v[28:31], v[174:177], v[220:223], v[28:31]
	v_mfma_f32_16x16x32_bf16 v[16:19], v[136:139], v[238:241], v[16:19]
	v_mfma_f32_16x16x32_bf16 v[12:15], v[174:177], v[238:241], v[12:15]
	v_mfma_f32_16x16x32_bf16 v[56:59], v[178:181], v[200:203], v[56:59]
	v_mfma_f32_16x16x32_bf16 v[52:55], v[192:195], v[200:203], v[52:55]
	v_mfma_f32_16x16x32_bf16 v[40:43], v[178:181], v[208:211], v[40:43]
	v_mfma_f32_16x16x32_bf16 v[36:39], v[192:195], v[208:211], v[36:39]
	v_mfma_f32_16x16x32_bf16 v[24:27], v[178:181], v[216:219], v[24:27]
	v_mfma_f32_16x16x32_bf16 v[20:23], v[192:195], v[216:219], v[20:23]
	v_mfma_f32_16x16x32_bf16 v[8:11], v[178:181], v[224:227], v[8:11]
	v_mfma_f32_16x16x32_bf16 v[4:7], v[192:195], v[224:227], v[4:7]
	v_mfma_f32_16x16x32_bf16 v[56:59], v[188:191], v[204:207], v[56:59]
	v_mfma_f32_16x16x32_bf16 v[52:55], v[196:199], v[204:207], v[52:55]
	v_mfma_f32_16x16x32_bf16 v[40:43], v[188:191], v[212:215], v[40:43]
	v_mfma_f32_16x16x32_bf16 v[36:39], v[196:199], v[212:215], v[36:39]
	v_mfma_f32_16x16x32_bf16 v[24:27], v[188:191], v[220:223], v[24:27]
	v_mfma_f32_16x16x32_bf16 v[20:23], v[196:199], v[220:223], v[20:23]
	v_mfma_f32_16x16x32_bf16 v[8:11], v[188:191], v[238:241], v[8:11]
	v_mfma_f32_16x16x32_bf16 v[4:7], v[196:199], v[238:241], v[4:7]
	s_barrier
	s_add_u32 s6, s6, 0x100
	s_addc_u32 s7, s7, 0
	s_add_u32 s78, s78, 0x100
	s_addc_u32 s79, s79, 0
	s_cmp_ge_u32 s80, s69
	s_mov_b32 s58, s80
	s_cbranch_scc0 .LBB0_476
	s_branch .Lpeel_exit2
.LBB0_476:
	s_add_i32 s80, s58, 2
	s_add_u32 s81, s6, 0x80
	s_addc_u32 s59, s7, 0
	s_add_i32 s87, 0, 0x10000
	s_cmp_eq_u32 s70, s58
	s_cselect_b32 s59, s55, s59
	s_cselect_b32 s58, s54, s81
	v_add_u32_e32 v144, s87, v184
	s_cselect_b32 s83, s57, s79
	s_cselect_b32 s82, s56, s78
	s_add_i32 s81, 0, 0x14000
	ds_read_b128 v[132:135], v144
	ds_read_b128 v[136:139], v144 offset:1024
	ds_read_b128 v[140:143], v144 offset:2048
	ds_read_b128 v[174:177], v144 offset:3072
	v_add_u32_e32 v144, s81, v184
	ds_read_b128 v[178:181], v144
	ds_read_b128 v[188:191], v144 offset:1024
	ds_read_b128 v[192:195], v144 offset:2048
	ds_read_b128 v[196:199], v144 offset:3072
	v_lshl_add_u64 v[144:145], s[6:7], 0, v[170:171]
	s_add_i32 m0, s62, 0xc000
	ds_read_b128 v[200:203], v186
	ds_read_b128 v[204:207], v186 offset:1024
	ds_read_b128 v[208:211], v186 offset:2048
	ds_read_b128 v[212:215], v186 offset:3072
	ds_read_b128 v[216:219], v186 offset:4096
	ds_read_b128 v[220:223], v186 offset:5120
	ds_read_b128 v[224:227], v186 offset:6144
	ds_read_b128 v[238:241], v186 offset:7168
	global_load_lds_dwordx4 v[144:145], off
	v_lshl_add_u64 v[144:145], s[6:7], 0, v[172:173]
	s_add_i32 m0, s62, 0xe000
	s_nop 0
	global_load_lds_dwordx4 v[144:145], off
	s_waitcnt vmcnt(8)
	s_waitcnt lgkmcnt(0)
	s_barrier
; #define PG8_STAGE(bufoff, gbase, voff) do { _Pragma("unroll") for (int _i = 0; _i < 2; ++_i) \
;         __builtin_amdgcn_global_load_lds((const unsigned*)((const char*)(gbase) + (voff)[_i]), (PG8_LAS unsigned*)(lds + (bufoff) + ldsw + _i * 8192), 16, 0, 0); } while (0)
; #define PG8_LDA(dst, b, h) do { _Pragma("unroll") for (int m = 0; m < 4; ++m) _Pragma("unroll") for (int k = 0; k < 2; ++k) dst[m][k] = *(const PG8_LAS bf16x8*)(lds + PG8_SA(b, h) + aoff + m * 2048 + k * 1024); } while (0)
; #define PG8_LDB(dst, b, h) do { _Pragma("unroll") for (int n = 0; n < 2; ++n) _Pragma("unroll") for (int k = 0; k < 2; ++k) dst[n][k] = *(const PG8_LAS bf16x8*)(lds + PG8_SB(b, h) + boff + n * 2048 + k * 1024); } while (0)
; #define PG8_MMA(ai, bj, At, Bt) do { __builtin_amdgcn_s_setprio(1); _Pragma("unroll") for (int m = 0; m < 4; ++m) _Pragma("unroll") for (int n = 0; n < 2; ++n) _Pragma("unroll") for (int k = 0; k < 2; ++k) \
;         acc[ai][bj][m][n] = __builtin_amdgcn_mfma_f32_16x16x32_bf16(Bt[n][k], At[m][k], acc[ai][bj][m][n], 0, 0, 0); __builtin_amdgcn_s_setprio(0); } while (0)
; #define PG8_WAIT_V(n) asm volatile("s_waitcnt vmcnt(" #n ")" ::: "memory")
; #define PG8_WAIT_L(n) asm volatile("s_waitcnt lgkmcnt(" #n ")" ::: "memory")
; #define PG8_BAR __builtin_amdgcn_s_barrier()
; #define PG8_SCHED __builtin_amdgcn_sched_barrier(0)
; template <class Epi, class Sched, bool ALIGN_EPI = false, bool SP2 = false>
; __device__ __forceinline__ void gemm_phase(PG8_LAS unsigned char* lds, const Gemm g, const Sched& S, const Epi& E, const int tid) {
;     ...
;             PG8_WAIT_V(8); PG8_WAIT_L(0); PG8_BAR; PG8_MMA(0, 0, At, B0); PG8_MMA(0, 1, At, B1); PG8_BAR; PG8_SCHED;
;             PG8_LDA(At, 0, 1); PG8_STAGE(PG8_SB(0, 0), b2, voffB); PG8_STAGE(PG8_SB(0, 1), b2 + hstep, voffB); PG8_STAGE(PG8_SA(0, 0), a2, voffA);
;             PG8_WAIT_V(8); PG8_WAIT_L(0); PG8_BAR; PG8_MMA(1, 0, At, B0); PG8_MMA(1, 1, At, B1); PG8_BAR; PG8_SCHED;
;             PG8_LDB(B0, 1, 0); PG8_LDB(B1, 1, 1); PG8_SCHED; PG8_LDA(At, 1, 0); PG8_STAGE(PG8_SA(0, 1), a2 + hstep, voffA);
;             PG8_WAIT_V(8); PG8_WAIT_L(0); PG8_BAR; PG8_MMA(0, 0, At, B0); PG8_MMA(0, 1, At, B1); PG8_BAR; PG8_SCHED;
	s_waitcnt lgkmcnt(0)
	v_mfma_f32_16x16x32_bf16 v[128:131], v[132:135], v[200:203], v[128:131]
	v_mfma_f32_16x16x32_bf16 v[124:127], v[140:143], v[200:203], v[124:127]
	v_mfma_f32_16x16x32_bf16 v[112:115], v[132:135], v[208:211], v[112:115]
	v_mfma_f32_16x16x32_bf16 v[108:111], v[140:143], v[208:211], v[108:111]
	v_mfma_f32_16x16x32_bf16 v[96:99], v[132:135], v[216:219], v[96:99]
	v_mfma_f32_16x16x32_bf16 v[92:95], v[140:143], v[216:219], v[92:95]
	v_mfma_f32_16x16x32_bf16 v[80:83], v[132:135], v[224:227], v[80:83]
	v_mfma_f32_16x16x32_bf16 v[76:79], v[140:143], v[224:227], v[76:79]
	v_mfma_f32_16x16x32_bf16 v[128:131], v[136:139], v[204:207], v[128:131]
	v_mfma_f32_16x16x32_bf16 v[124:127], v[174:177], v[204:207], v[124:127]
	v_mfma_f32_16x16x32_bf16 v[112:115], v[136:139], v[212:215], v[112:115]
	v_mfma_f32_16x16x32_bf16 v[108:111], v[174:177], v[212:215], v[108:111]
	v_mfma_f32_16x16x32_bf16 v[96:99], v[136:139], v[220:223], v[96:99]
	v_mfma_f32_16x16x32_bf16 v[92:95], v[174:177], v[220:223], v[92:95]
	v_mfma_f32_16x16x32_bf16 v[80:83], v[136:139], v[238:241], v[80:83]
	v_mfma_f32_16x16x32_bf16 v[76:79], v[174:177], v[238:241], v[76:79]
	v_mfma_f32_16x16x32_bf16 v[120:123], v[178:181], v[200:203], v[120:123]
	v_mfma_f32_16x16x32_bf16 v[116:119], v[192:195], v[200:203], v[116:119]
	v_mfma_f32_16x16x32_bf16 v[104:107], v[178:181], v[208:211], v[104:107]
	v_mfma_f32_16x16x32_bf16 v[100:103], v[192:195], v[208:211], v[100:103]
	v_mfma_f32_16x16x32_bf16 v[88:91], v[178:181], v[216:219], v[88:91]
	v_mfma_f32_16x16x32_bf16 v[84:87], v[192:195], v[216:219], v[84:87]
	v_mfma_f32_16x16x32_bf16 v[72:75], v[178:181], v[224:227], v[72:75]
	v_mfma_f32_16x16x32_bf16 v[68:71], v[192:195], v[224:227], v[68:71]
	v_mfma_f32_16x16x32_bf16 v[120:123], v[188:191], v[204:207], v[120:123]
	v_mfma_f32_16x16x32_bf16 v[116:119], v[196:199], v[204:207], v[116:119]
	v_mfma_f32_16x16x32_bf16 v[104:107], v[188:191], v[212:215], v[104:107]
	v_mfma_f32_16x16x32_bf16 v[100:103], v[196:199], v[212:215], v[100:103]
	v_mfma_f32_16x16x32_bf16 v[88:91], v[188:191], v[220:223], v[88:91]
	v_mfma_f32_16x16x32_bf16 v[84:87], v[196:199], v[220:223], v[84:87]
	v_mfma_f32_16x16x32_bf16 v[72:75], v[188:191], v[238:241], v[72:75]
	v_mfma_f32_16x16x32_bf16 v[68:71], v[196:199], v[238:241], v[68:71]
	s_barrier
	s_add_i32 s87, s87, s61
	v_lshl_add_u64 v[144:145], s[82:83], 0, v[146:147]
	s_mov_b32 m0, s87
	ds_read_b128 v[200:203], v186 offset:16384
	ds_read_b128 v[204:207], v186 offset:17408
	ds_read_b128 v[208:211], v186 offset:18432
	ds_read_b128 v[212:215], v186 offset:19456
	ds_read_b128 v[216:219], v186 offset:20480
	ds_read_b128 v[220:223], v186 offset:21504
	ds_read_b128 v[224:227], v186 offset:22528
	ds_read_b128 v[238:241], v186 offset:23552
	global_load_lds_dwordx4 v[144:145], off
	s_add_i32 m0, s87, 0x2000
	v_lshl_add_u64 v[242:243], s[82:83], 0, v[168:169]
	s_add_u32 s82, s82, s14
	s_addc_u32 s83, s83, 0
	s_add_i32 s81, s81, s61
	global_load_lds_dwordx4 v[242:243], off
	v_lshl_add_u64 v[244:245], s[82:83], 0, v[146:147]
	s_mov_b32 m0, s81
	v_lshl_add_u64 v[246:247], s[82:83], 0, v[168:169]
	global_load_lds_dwordx4 v[244:245], off
	s_add_i32 m0, s81, 0x2000
	v_lshl_add_u64 v[248:249], s[58:59], 0, v[0:1]
	global_load_lds_dwordx4 v[246:247], off
	s_mov_b32 m0, s62
	v_lshl_add_u64 v[148:149], s[58:59], 0, v[166:167]
	global_load_lds_dwordx4 v[248:249], off
	s_mov_b32 m0, s63
	s_nop 0
	global_load_lds_dwordx4 v[148:149], off
	s_waitcnt vmcnt(8)
	s_waitcnt lgkmcnt(0)
	s_barrier
	s_waitcnt lgkmcnt(0)
	v_mfma_f32_16x16x32_bf16 v[64:67], v[132:135], v[200:203], v[64:67]
	v_mfma_f32_16x16x32_bf16 v[60:63], v[140:143], v[200:203], v[60:63]
	v_mfma_f32_16x16x32_bf16 v[48:51], v[132:135], v[208:211], v[48:51]
	v_mfma_f32_16x16x32_bf16 v[44:47], v[140:143], v[208:211], v[44:47]
	v_mfma_f32_16x16x32_bf16 v[32:35], v[132:135], v[216:219], v[32:35]
	v_mfma_f32_16x16x32_bf16 v[28:31], v[140:143], v[216:219], v[28:31]
	v_mfma_f32_16x16x32_bf16 v[16:19], v[132:135], v[224:227], v[16:19]
	v_mfma_f32_16x16x32_bf16 v[12:15], v[140:143], v[224:227], v[12:15]
	v_mfma_f32_16x16x32_bf16 v[64:67], v[136:139], v[204:207], v[64:67]
	v_mfma_f32_16x16x32_bf16 v[60:63], v[174:177], v[204:207], v[60:63]
	v_mfma_f32_16x16x32_bf16 v[48:51], v[136:139], v[212:215], v[48:51]
	v_mfma_f32_16x16x32_bf16 v[44:47], v[174:177], v[212:215], v[44:47]
	v_mfma_f32_16x16x32_bf16 v[32:35], v[136:139], v[220:223], v[32:35]
	v_mfma_f32_16x16x32_bf16 v[28:31], v[174:177], v[220:223], v[28:31]
	v_mfma_f32_16x16x32_bf16 v[16:19], v[136:139], v[238:241], v[16:19]
	v_mfma_f32_16x16x32_bf16 v[12:15], v[174:177], v[238:241], v[12:15]
	v_mfma_f32_16x16x32_bf16 v[56:59], v[178:181], v[200:203], v[56:59]
	v_mfma_f32_16x16x32_bf16 v[52:55], v[192:195], v[200:203], v[52:55]
	v_mfma_f32_16x16x32_bf16 v[40:43], v[178:181], v[208:211], v[40:43]
	v_mfma_f32_16x16x32_bf16 v[36:39], v[192:195], v[208:211], v[36:39]
	v_mfma_f32_16x16x32_bf16 v[24:27], v[178:181], v[216:219], v[24:27]
	v_mfma_f32_16x16x32_bf16 v[20:23], v[192:195], v[216:219], v[20:23]
	v_mfma_f32_16x16x32_bf16 v[8:11], v[178:181], v[224:227], v[8:11]
	v_mfma_f32_16x16x32_bf16 v[4:7], v[192:195], v[224:227], v[4:7]
	v_mfma_f32_16x16x32_bf16 v[56:59], v[188:191], v[204:207], v[56:59]
	v_mfma_f32_16x16x32_bf16 v[52:55], v[196:199], v[204:207], v[52:55]
	v_mfma_f32_16x16x32_bf16 v[40:43], v[188:191], v[212:215], v[40:43]
	v_mfma_f32_16x16x32_bf16 v[36:39], v[196:199], v[212:215], v[36:39]
	v_mfma_f32_16x16x32_bf16 v[24:27], v[188:191], v[220:223], v[24:27]
	v_mfma_f32_16x16x32_bf16 v[20:23], v[196:199], v[220:223], v[20:23]
	v_mfma_f32_16x16x32_bf16 v[8:11], v[188:191], v[238:241], v[8:11]
	v_mfma_f32_16x16x32_bf16 v[4:7], v[196:199], v[238:241], v[4:7]
	s_barrier
; #define PG8_STAGE(bufoff, gbase, voff) do { _Pragma("unroll") for (int _i = 0; _i < 2; ++_i) \
;         __builtin_amdgcn_global_load_lds((const unsigned*)((const char*)(gbase) + (voff)[_i]), (PG8_LAS unsigned*)(lds + (bufoff) + ldsw + _i * 8192), 16, 0, 0); } while (0)
; #define PG8_LDA(dst, b, h) do { _Pragma("unroll") for (int m = 0; m < 4; ++m) _Pragma("unroll") for (int k = 0; k < 2; ++k) dst[m][k] = *(const PG8_LAS bf16x8*)(lds + PG8_SA(b, h) + aoff + m * 2048 + k * 1024); } while (0)
; #define PG8_LDB(dst, b, h) do { _Pragma("unroll") for (int n = 0; n < 2; ++n) _Pragma("unroll") for (int k = 0; k < 2; ++k) dst[n][k] = *(const PG8_LAS bf16x8*)(lds + PG8_SB(b, h) + boff + n * 2048 + k * 1024); } while (0)
; #define PG8_MMA(ai, bj, At, Bt) do { __builtin_amdgcn_s_setprio(1); _Pragma("unroll") for (int m = 0; m < 4; ++m) _Pragma("unroll") for (int n = 0; n < 2; ++n) _Pragma("unroll") for (int k = 0; k < 2; ++k) \
;         acc[ai][bj][m][n] = __builtin_amdgcn_mfma_f32_16x16x32_bf16(Bt[n][k], At[m][k], acc[ai][bj][m][n], 0, 0, 0); __builtin_amdgcn_s_setprio(0); } while (0)
; #define PG8_WAIT_V(n) asm volatile("s_waitcnt vmcnt(" #n ")" ::: "memory")
; #define PG8_WAIT_L(n) asm volatile("s_waitcnt lgkmcnt(" #n ")" ::: "memory")
; #define PG8_BAR __builtin_amdgcn_s_barrier()
; #define PG8_SCHED __builtin_amdgcn_sched_barrier(0)
; template <class Epi, class Sched, bool ALIGN_EPI = false, bool SP2 = false>
; __device__ __forceinline__ void gemm_phase(PG8_LAS unsigned char* lds, const Gemm g, const Sched& S, const Epi& E, const int tid) {
;     ...
;             PG8_LDB(B0, 1, 0); PG8_LDB(B1, 1, 1); PG8_SCHED; PG8_LDA(At, 1, 0); PG8_STAGE(PG8_SA(0, 1), a2 + hstep, voffA);
;             PG8_WAIT_V(8); PG8_WAIT_L(0); PG8_BAR; PG8_MMA(0, 0, At, B0); PG8_MMA(0, 1, At, B1); PG8_BAR; PG8_SCHED;
;             PG8_LDA(At, 1, 1); PG8_STAGE(PG8_SB(1, 0), b3, voffB); PG8_STAGE(PG8_SB(1, 1), b3 + hstep, voffB); PG8_STAGE(PG8_SA(1, 0), a3, voffA);
;             PG8_WAIT_V(8); PG8_WAIT_L(0); PG8_BAR; PG8_MMA(1, 0, At, B0); PG8_MMA(1, 1, At, B1); PG8_BAR; PG8_SCHED;
	s_add_i32 s81, 0, 0x18000
	v_add_u32_e32 v150, s81, v184
	s_add_i32 s82, 0, 0x1c000
	ds_read_b128 v[132:135], v150
	ds_read_b128 v[136:139], v150 offset:1024
	ds_read_b128 v[140:143], v150 offset:2048
	ds_read_b128 v[174:177], v150 offset:3072
	v_add_u32_e32 v150, s82, v184
	ds_read_b128 v[178:181], v150
	ds_read_b128 v[188:191], v150 offset:1024
	ds_read_b128 v[192:195], v150 offset:2048
	ds_read_b128 v[196:199], v150 offset:3072
	s_add_u32 s58, s58, s14
	s_addc_u32 s59, s59, 0
	s_mov_b32 m0, s64
	v_lshl_add_u64 v[150:151], s[58:59], 0, v[0:1]
	ds_read_b128 v[200:203], v186 offset:32768
	ds_read_b128 v[204:207], v186 offset:33792
	ds_read_b128 v[208:211], v186 offset:34816
	ds_read_b128 v[212:215], v186 offset:35840
	ds_read_b128 v[216:219], v186 offset:36864
	ds_read_b128 v[220:223], v186 offset:37888
	ds_read_b128 v[224:227], v186 offset:38912
	ds_read_b128 v[238:241], v186 offset:39936
	global_load_lds_dwordx4 v[150:151], off
	v_lshl_add_u64 v[150:151], s[58:59], 0, v[166:167]
	s_mov_b32 m0, s65
	s_nop 0
	global_load_lds_dwordx4 v[150:151], off
	s_waitcnt vmcnt(8)
	s_waitcnt lgkmcnt(0)
	s_barrier
	s_waitcnt lgkmcnt(0)
	v_mfma_f32_16x16x32_bf16 v[128:131], v[132:135], v[200:203], v[128:131]
	v_mfma_f32_16x16x32_bf16 v[124:127], v[140:143], v[200:203], v[124:127]
	v_mfma_f32_16x16x32_bf16 v[112:115], v[132:135], v[208:211], v[112:115]
	v_mfma_f32_16x16x32_bf16 v[108:111], v[140:143], v[208:211], v[108:111]
	v_mfma_f32_16x16x32_bf16 v[96:99], v[132:135], v[216:219], v[96:99]
	v_mfma_f32_16x16x32_bf16 v[92:95], v[140:143], v[216:219], v[92:95]
	v_mfma_f32_16x16x32_bf16 v[80:83], v[132:135], v[224:227], v[80:83]
	v_mfma_f32_16x16x32_bf16 v[76:79], v[140:143], v[224:227], v[76:79]
	v_mfma_f32_16x16x32_bf16 v[128:131], v[136:139], v[204:207], v[128:131]
	v_mfma_f32_16x16x32_bf16 v[124:127], v[174:177], v[204:207], v[124:127]
	v_mfma_f32_16x16x32_bf16 v[112:115], v[136:139], v[212:215], v[112:115]
	v_mfma_f32_16x16x32_bf16 v[108:111], v[174:177], v[212:215], v[108:111]
	v_mfma_f32_16x16x32_bf16 v[96:99], v[136:139], v[220:223], v[96:99]
	v_mfma_f32_16x16x32_bf16 v[92:95], v[174:177], v[220:223], v[92:95]
	v_mfma_f32_16x16x32_bf16 v[80:83], v[136:139], v[238:241], v[80:83]
	v_mfma_f32_16x16x32_bf16 v[76:79], v[174:177], v[238:241], v[76:79]
	v_mfma_f32_16x16x32_bf16 v[120:123], v[178:181], v[200:203], v[120:123]
	v_mfma_f32_16x16x32_bf16 v[116:119], v[192:195], v[200:203], v[116:119]
	v_mfma_f32_16x16x32_bf16 v[104:107], v[178:181], v[208:211], v[104:107]
	v_mfma_f32_16x16x32_bf16 v[100:103], v[192:195], v[208:211], v[100:103]
	v_mfma_f32_16x16x32_bf16 v[88:91], v[178:181], v[216:219], v[88:91]
	v_mfma_f32_16x16x32_bf16 v[84:87], v[192:195], v[216:219], v[84:87]
	v_mfma_f32_16x16x32_bf16 v[72:75], v[178:181], v[224:227], v[72:75]
	v_mfma_f32_16x16x32_bf16 v[68:71], v[192:195], v[224:227], v[68:71]
	v_mfma_f32_16x16x32_bf16 v[120:123], v[188:191], v[204:207], v[120:123]
	v_mfma_f32_16x16x32_bf16 v[116:119], v[196:199], v[204:207], v[116:119]
	v_mfma_f32_16x16x32_bf16 v[104:107], v[188:191], v[212:215], v[104:107]
	v_mfma_f32_16x16x32_bf16 v[100:103], v[196:199], v[212:215], v[100:103]
	v_mfma_f32_16x16x32_bf16 v[88:91], v[188:191], v[220:223], v[88:91]
	v_mfma_f32_16x16x32_bf16 v[84:87], v[196:199], v[220:223], v[84:87]
	v_mfma_f32_16x16x32_bf16 v[72:75], v[188:191], v[238:241], v[72:75]
	v_mfma_f32_16x16x32_bf16 v[68:71], v[196:199], v[238:241], v[68:71]
	s_barrier
	s_add_i32 s58, s81, s61
	v_lshl_add_u64 v[144:145], v[144:145], 0, s[0:1]
	s_mov_b32 m0, s58
	ds_read_b128 v[200:203], v186 offset:49152
	ds_read_b128 v[204:207], v186 offset:50176
	ds_read_b128 v[208:211], v186 offset:51200
	ds_read_b128 v[212:215], v186 offset:52224
	ds_read_b128 v[216:219], v186 offset:53248
	ds_read_b128 v[220:223], v186 offset:54272
	ds_read_b128 v[224:227], v186 offset:55296
	ds_read_b128 v[238:241], v186 offset:56320
	global_load_lds_dwordx4 v[144:145], off
	v_lshl_add_u64 v[144:145], v[242:243], 0, s[0:1]
	s_add_i32 m0, s58, 0x2000
	s_add_i32 s58, s82, s61
	global_load_lds_dwordx4 v[144:145], off
	v_lshl_add_u64 v[144:145], v[244:245], 0, s[0:1]
	s_mov_b32 m0, s58
	s_nop 0
	global_load_lds_dwordx4 v[144:145], off
	v_lshl_add_u64 v[144:145], v[246:247], 0, s[0:1]
	s_add_i32 m0, s58, 0x2000
	s_nop 0
	global_load_lds_dwordx4 v[144:145], off
	v_lshl_add_u64 v[144:145], v[248:249], 0, s[0:1]
	s_mov_b32 m0, s66
	s_nop 0
	global_load_lds_dwordx4 v[144:145], off
	v_lshl_add_u64 v[144:145], v[148:149], 0, s[0:1]
	s_mov_b32 m0, s67
	s_nop 0
	global_load_lds_dwordx4 v[144:145], off
	s_waitcnt vmcnt(8)
	s_waitcnt lgkmcnt(0)
	s_barrier
	s_waitcnt lgkmcnt(0)
	v_mfma_f32_16x16x32_bf16 v[64:67], v[132:135], v[200:203], v[64:67]
	v_mfma_f32_16x16x32_bf16 v[60:63], v[140:143], v[200:203], v[60:63]
	v_mfma_f32_16x16x32_bf16 v[48:51], v[132:135], v[208:211], v[48:51]
	v_mfma_f32_16x16x32_bf16 v[44:47], v[140:143], v[208:211], v[44:47]
	v_mfma_f32_16x16x32_bf16 v[32:35], v[132:135], v[216:219], v[32:35]
	v_mfma_f32_16x16x32_bf16 v[28:31], v[140:143], v[216:219], v[28:31]
	v_mfma_f32_16x16x32_bf16 v[16:19], v[132:135], v[224:227], v[16:19]
	v_mfma_f32_16x16x32_bf16 v[12:15], v[140:143], v[224:227], v[12:15]
	v_mfma_f32_16x16x32_bf16 v[64:67], v[136:139], v[204:207], v[64:67]
	v_mfma_f32_16x16x32_bf16 v[60:63], v[174:177], v[204:207], v[60:63]
	v_mfma_f32_16x16x32_bf16 v[48:51], v[136:139], v[212:215], v[48:51]
	v_mfma_f32_16x16x32_bf16 v[44:47], v[174:177], v[212:215], v[44:47]
	v_mfma_f32_16x16x32_bf16 v[32:35], v[136:139], v[220:223], v[32:35]
	v_mfma_f32_16x16x32_bf16 v[28:31], v[174:177], v[220:223], v[28:31]
	v_mfma_f32_16x16x32_bf16 v[16:19], v[136:139], v[238:241], v[16:19]
	v_mfma_f32_16x16x32_bf16 v[12:15], v[174:177], v[238:241], v[12:15]
	v_mfma_f32_16x16x32_bf16 v[56:59], v[178:181], v[200:203], v[56:59]
	v_mfma_f32_16x16x32_bf16 v[52:55], v[192:195], v[200:203], v[52:55]
	v_mfma_f32_16x16x32_bf16 v[40:43], v[178:181], v[208:211], v[40:43]
	v_mfma_f32_16x16x32_bf16 v[36:39], v[192:195], v[208:211], v[36:39]
	v_mfma_f32_16x16x32_bf16 v[24:27], v[178:181], v[216:219], v[24:27]
	v_mfma_f32_16x16x32_bf16 v[20:23], v[192:195], v[216:219], v[20:23]
	v_mfma_f32_16x16x32_bf16 v[8:11], v[178:181], v[224:227], v[8:11]
	v_mfma_f32_16x16x32_bf16 v[4:7], v[192:195], v[224:227], v[4:7]
	v_mfma_f32_16x16x32_bf16 v[56:59], v[188:191], v[204:207], v[56:59]
	v_mfma_f32_16x16x32_bf16 v[52:55], v[196:199], v[204:207], v[52:55]
	v_mfma_f32_16x16x32_bf16 v[40:43], v[188:191], v[212:215], v[40:43]
	v_mfma_f32_16x16x32_bf16 v[36:39], v[196:199], v[212:215], v[36:39]
	v_mfma_f32_16x16x32_bf16 v[24:27], v[188:191], v[220:223], v[24:27]
	v_mfma_f32_16x16x32_bf16 v[20:23], v[196:199], v[220:223], v[20:23]
	v_mfma_f32_16x16x32_bf16 v[8:11], v[188:191], v[238:241], v[8:11]
	v_mfma_f32_16x16x32_bf16 v[4:7], v[196:199], v[238:241], v[4:7]
	s_barrier
	s_add_u32 s6, s6, 0x100
	s_addc_u32 s7, s7, 0
	s_add_u32 s78, s78, 0x100
	s_addc_u32 s79, s79, 0
	s_cmp_ge_u32 s80, s69
	s_mov_b32 s58, s80
	s_cbranch_scc0 .LBB0_476
; #define PG8_BAR __builtin_amdgcn_s_barrier()
; template <class Epi, class Sched, bool ALIGN_EPI = false, bool SP2 = false>
; __device__ __forceinline__ void gemm_phase(PG8_LAS unsigned char* lds, const Gemm g, const Sched& S, const Epi& E, const int tid) {
;     ...
;         if constexpr (ALIGN_EPI) { if (wr == 0) PG8_BAR; }
.Lpeel_exit2:
	s_and_b64 vcc, exec, s[50:51]
	s_cbranch_vccz .LBB0_479
	s_barrier

; #define PG8_STAGE(bufoff, gbase, voff) do { _Pragma("unroll") for (int _i = 0; _i < 2; ++_i) \
;         __builtin_amdgcn_global_load_lds((const unsigned*)((const char*)(gbase) + (voff)[_i]), (PG8_LAS unsigned*)(lds + (bufoff) + ldsw + _i * 8192), 16, 0, 0); } while (0)
; #define PG8_LDA(dst, b, h) do { _Pragma("unroll") for (int m = 0; m < 4; ++m) _Pragma("unroll") for (int k = 0; k < 2; ++k) dst[m][k] = *(const PG8_LAS bf16x8*)(lds + PG8_SA(b, h) + aoff + m * 2048 + k * 1024); } while (0)
; #define PG8_LDB(dst, b, h) do { _Pragma("unroll") for (int n = 0; n < 2; ++n) _Pragma("unroll") for (int k = 0; k < 2; ++k) dst[n][k] = *(const PG8_LAS bf16x8*)(lds + PG8_SB(b, h) + boff + n * 2048 + k * 1024); } while (0)
; #define PG8_WAIT_V(n) asm volatile("s_waitcnt vmcnt(" #n ")" ::: "memory")
; #define PG8_WAIT_L(n) asm volatile("s_waitcnt lgkmcnt(" #n ")" ::: "memory")
; #define PG8_BAR __builtin_amdgcn_s_barrier()
; #define PG8_SCHED __builtin_amdgcn_sched_barrier(0)
; template <class Epi, class Sched, bool ALIGN_EPI = false, bool SP2 = false>
; __device__ __forceinline__ void gemm_phase(PG8_LAS unsigned char* lds, const Gemm g, const Sched& S, const Epi& E, const int tid) {
;     ...
;         const bool has_next = S.next(ui + 1, nxt);
;         const char* nA = has_next ? (const char*)g.A + (size_t)nxt.pm * tstep : cA; const char* nB = has_next ? (const char*)g.Bt + (size_t)nxt.pn * tstep : cB;
;         for (int t = 0; t < nt; t += 2) {
;             const bool last = (t == nt - 2);
;             const char* a1 = cA + (size_t)(t + 1) * kstep;
;             const char* a2 = last ? nA : cA + (size_t)(t + 2) * kstep; const char* b2 = last ? nB : cB + (size_t)(t + 2) * kstep;
;             const char* a3 = a2 + kstep; const char* b3 = b2 + kstep;
;             if (last && has_next) S.a_ready(nxt);
;             if constexpr (SP2) {
;             PG8_LDB(B0, 0, 0); PG8_LDB(B1, 0, 1); PG8_SCHED; PG8_LDA(At, 0, 0); PG8_STAGE(PG8_SA(1, 1), a1 + hstep, voffA);
;             PG8_WAIT_V(8); PG8_WAIT_L(0); PG8_BAR; PG8_MMA(0, 0, At, B0); PG8_MMA(0, 1, At, B1); PG8_BAR; PG8_SCHED;
;             PG8_LDA(At, 0, 1); PG8_STAGE(PG8_SB(0, 0), b2, voffB); PG8_STAGE(PG8_SB(0, 1), b2 + hstep, voffB); PG8_STAGE(PG8_SA(0, 0), a2, voffA);
;             PG8_WAIT_V(8); PG8_WAIT_L(0); PG8_BAR; PG8_MMA(1, 0, At, B0); PG8_MMA(1, 1, At, B1); PG8_BAR; PG8_SCHED;
.LBB0_521:
	s_ashr_i32 s13, s12, 31
	s_lshl_b64 s[14:15], s[12:13], 19
	s_add_u32 s14, s26, s14
	s_addc_u32 s15, s27, s15
	s_and_b64 s[16:17], s[2:3], exec
	s_cselect_b32 s13, s15, s19
	s_cselect_b32 s47, s14, s18
	s_ashr_i32 s11, s10, 31
	s_lshl_b64 s[16:17], s[10:11], 19
	s_add_u32 s16, s34, s16
	s_addc_u32 s17, s36, s17
	s_and_b64 s[22:23], s[2:3], exec
	s_cselect_b32 s11, s17, s21
	s_cselect_b32 s48, s16, s20
	s_add_u32 s18, s18, 0x40080
	s_addc_u32 s19, s19, 0
	s_add_u32 s49, s20, 0x100
	v_mov_b32_e32 v4, 0
	s_addc_u32 s50, s21, 0
	s_mov_b32 s51, -2
	s_add_u32 s20, s18, 0xfffc0080
	s_addc_u32 s21, s19, -1
	s_add_i32 s52, 0, 0x10000
	s_cmp_eq_u32 s51, 12
	s_cselect_b32 s23, s13, s21
	s_cselect_b32 s22, s47, s20
	v_add_u32_e32 v148, s52, v146
	s_cselect_b32 s21, s11, s50
	s_cselect_b32 s20, s48, s49
	s_add_i32 s54, 0, 0x14000
	ds_read_b128 v[142:145], v148
	ds_read_b128 v[166:169], v148 offset:1024
	ds_read_b128 v[170:173], v148 offset:2048
	ds_read_b128 v[174:177], v148 offset:3072
	v_add_u32_e32 v148, s54, v146
	ds_read_b128 v[178:181], v148
	ds_read_b128 v[182:185], v148 offset:1024
	ds_read_b128 v[186:189], v148 offset:2048
	ds_read_b128 v[190:193], v148 offset:3072
	v_lshl_add_u64 v[226:227], s[18:19], 0, v[138:139]
	s_add_i32 m0, s38, 0xc000
	ds_read_b128 v[194:197], v153
	ds_read_b128 v[198:201], v153 offset:1024
	ds_read_b128 v[202:205], v153 offset:2048
	ds_read_b128 v[206:209], v153 offset:3072
	ds_read_b128 v[210:213], v153 offset:4096
	ds_read_b128 v[214:217], v153 offset:5120
	ds_read_b128 v[218:221], v153 offset:6144
	ds_read_b128 v[222:225], v153 offset:7168
	global_load_lds_dwordx4 v[226:227], off
	v_lshl_add_u64 v[226:227], s[18:19], 0, v[140:141]
	s_add_i32 m0, s38, 0xe000
	s_nop 0
	global_load_lds_dwordx4 v[226:227], off
	s_waitcnt vmcnt(8)
	s_waitcnt lgkmcnt(0)
	s_barrier
	s_waitcnt lgkmcnt(0)
	v_mfma_f32_16x16x32_bf16 v[128:131], v[142:145], v[194:197], 0
	v_mfma_f32_16x16x32_bf16 v[120:123], v[170:173], v[194:197], 0
	v_mfma_f32_16x16x32_bf16 v[112:115], v[142:145], v[202:205], 0
	v_mfma_f32_16x16x32_bf16 v[104:107], v[170:173], v[202:205], 0
	v_mfma_f32_16x16x32_bf16 v[96:99], v[142:145], v[210:213], 0
	v_mfma_f32_16x16x32_bf16 v[88:91], v[170:173], v[210:213], 0
	v_mfma_f32_16x16x32_bf16 v[80:83], v[142:145], v[218:221], 0
	v_mfma_f32_16x16x32_bf16 v[72:75], v[170:173], v[218:221], 0
	v_mfma_f32_16x16x32_bf16 v[128:131], v[166:169], v[198:201], v[128:131]
	v_mfma_f32_16x16x32_bf16 v[120:123], v[174:177], v[198:201], v[120:123]
	v_mfma_f32_16x16x32_bf16 v[112:115], v[166:169], v[206:209], v[112:115]
	v_mfma_f32_16x16x32_bf16 v[104:107], v[174:177], v[206:209], v[104:107]
	v_mfma_f32_16x16x32_bf16 v[96:99], v[166:169], v[214:217], v[96:99]
	v_mfma_f32_16x16x32_bf16 v[88:91], v[174:177], v[214:217], v[88:91]
	v_mfma_f32_16x16x32_bf16 v[80:83], v[166:169], v[222:225], v[80:83]
	v_mfma_f32_16x16x32_bf16 v[72:75], v[174:177], v[222:225], v[72:75]
	v_mfma_f32_16x16x32_bf16 v[124:127], v[178:181], v[194:197], 0
	v_mfma_f32_16x16x32_bf16 v[116:119], v[186:189], v[194:197], 0
	v_mfma_f32_16x16x32_bf16 v[108:111], v[178:181], v[202:205], 0
	v_mfma_f32_16x16x32_bf16 v[100:103], v[186:189], v[202:205], 0
	v_mfma_f32_16x16x32_bf16 v[92:95], v[178:181], v[210:213], 0
	v_mfma_f32_16x16x32_bf16 v[84:87], v[186:189], v[210:213], 0
	v_mfma_f32_16x16x32_bf16 v[76:79], v[178:181], v[218:221], 0
	v_mfma_f32_16x16x32_bf16 v[68:71], v[186:189], v[218:221], 0
	v_mfma_f32_16x16x32_bf16 v[124:127], v[182:185], v[198:201], v[124:127]
	v_mfma_f32_16x16x32_bf16 v[116:119], v[190:193], v[198:201], v[116:119]
	v_mfma_f32_16x16x32_bf16 v[108:111], v[182:185], v[206:209], v[108:111]
	v_mfma_f32_16x16x32_bf16 v[100:103], v[190:193], v[206:209], v[100:103]
	v_mfma_f32_16x16x32_bf16 v[92:95], v[182:185], v[214:217], v[92:95]
	v_mfma_f32_16x16x32_bf16 v[84:87], v[190:193], v[214:217], v[84:87]
	v_mfma_f32_16x16x32_bf16 v[76:79], v[182:185], v[222:225], v[76:79]
	v_mfma_f32_16x16x32_bf16 v[68:71], v[190:193], v[222:225], v[68:71]
	s_barrier
	s_add_i32 s52, s52, s37
	v_lshl_add_u64 v[226:227], s[20:21], 0, v[134:135]
	s_mov_b32 m0, s52
	ds_read_b128 v[194:197], v153 offset:16384
	ds_read_b128 v[198:201], v153 offset:17408
	ds_read_b128 v[202:205], v153 offset:18432
	ds_read_b128 v[206:209], v153 offset:19456
	ds_read_b128 v[210:213], v153 offset:20480
	ds_read_b128 v[214:217], v153 offset:21504
	ds_read_b128 v[218:221], v153 offset:22528
	ds_read_b128 v[222:225], v153 offset:23552
	global_load_lds_dwordx4 v[226:227], off
	s_add_i32 m0, s52, 0x2000
	s_add_u32 s52, s20, 0x40000
	v_lshl_add_u64 v[238:239], s[20:21], 0, v[0:1]
	s_addc_u32 s53, s21, 0
	s_add_i32 s54, s54, s37
	global_load_lds_dwordx4 v[238:239], off
	v_lshl_add_u64 v[240:241], s[52:53], 0, v[134:135]
	s_mov_b32 m0, s54
	v_lshl_add_u64 v[242:243], s[22:23], 0, v[132:133]
	global_load_lds_dwordx4 v[240:241], off
	v_lshl_add_u64 v[240:241], s[52:53], 0, v[0:1]
	s_add_i32 m0, s54, 0x2000
	s_nop 0
	global_load_lds_dwordx4 v[240:241], off
	v_lshl_add_u64 v[240:241], s[22:23], 0, v[136:137]
	s_mov_b32 m0, s38
	s_nop 0
	global_load_lds_dwordx4 v[240:241], off
	s_mov_b32 m0, s39
	s_nop 0
	global_load_lds_dwordx4 v[242:243], off
	s_waitcnt vmcnt(8)
	s_waitcnt lgkmcnt(0)
	s_barrier
; #define PG8_STAGE(bufoff, gbase, voff) do { _Pragma("unroll") for (int _i = 0; _i < 2; ++_i) \
;         __builtin_amdgcn_global_load_lds((const unsigned*)((const char*)(gbase) + (voff)[_i]), (PG8_LAS unsigned*)(lds + (bufoff) + ldsw + _i * 8192), 16, 0, 0); } while (0)
; #define PG8_LDA(dst, b, h) do { _Pragma("unroll") for (int m = 0; m < 4; ++m) _Pragma("unroll") for (int k = 0; k < 2; ++k) dst[m][k] = *(const PG8_LAS bf16x8*)(lds + PG8_SA(b, h) + aoff + m * 2048 + k * 1024); } while (0)
; #define PG8_LDB(dst, b, h) do { _Pragma("unroll") for (int n = 0; n < 2; ++n) _Pragma("unroll") for (int k = 0; k < 2; ++k) dst[n][k] = *(const PG8_LAS bf16x8*)(lds + PG8_SB(b, h) + boff + n * 2048 + k * 1024); } while (0)
; #define PG8_MMA(ai, bj, At, Bt) do { __builtin_amdgcn_s_setprio(1); _Pragma("unroll") for (int m = 0; m < 4; ++m) _Pragma("unroll") for (int n = 0; n < 2; ++n) _Pragma("unroll") for (int k = 0; k < 2; ++k) \
;         acc[ai][bj][m][n] = __builtin_amdgcn_mfma_f32_16x16x32_bf16(Bt[n][k], At[m][k], acc[ai][bj][m][n], 0, 0, 0); __builtin_amdgcn_s_setprio(0); } while (0)
; #define PG8_WAIT_V(n) asm volatile("s_waitcnt vmcnt(" #n ")" ::: "memory")
; #define PG8_WAIT_L(n) asm volatile("s_waitcnt lgkmcnt(" #n ")" ::: "memory")
; #define PG8_BAR __builtin_amdgcn_s_barrier()
; #define PG8_SCHED __builtin_amdgcn_sched_barrier(0)
; template <class Epi, class Sched, bool ALIGN_EPI = false, bool SP2 = false>
; __device__ __forceinline__ void gemm_phase(PG8_LAS unsigned char* lds, const Gemm g, const Sched& S, const Epi& E, const int tid) {
;     ...
;             PG8_WAIT_V(8); PG8_WAIT_L(0); PG8_BAR; PG8_MMA(1, 0, At, B0); PG8_MMA(1, 1, At, B1); PG8_BAR; PG8_SCHED;
;             PG8_LDB(B0, 1, 0); PG8_LDB(B1, 1, 1); PG8_SCHED; PG8_LDA(At, 1, 0); PG8_STAGE(PG8_SA(0, 1), a2 + hstep, voffA);
;             PG8_WAIT_V(8); PG8_WAIT_L(0); PG8_BAR; PG8_MMA(0, 0, At, B0); PG8_MMA(0, 1, At, B1); PG8_BAR; PG8_SCHED;
;             PG8_LDA(At, 1, 1); PG8_STAGE(PG8_SB(1, 0), b3, voffB); PG8_STAGE(PG8_SB(1, 1), b3 + hstep, voffB); PG8_STAGE(PG8_SA(1, 0), a3, voffA);
	s_waitcnt lgkmcnt(0)
	v_mfma_f32_16x16x32_bf16 v[64:67], v[142:145], v[194:197], 0
	v_mfma_f32_16x16x32_bf16 v[56:59], v[170:173], v[194:197], 0
	v_mfma_f32_16x16x32_bf16 v[48:51], v[142:145], v[202:205], 0
	v_mfma_f32_16x16x32_bf16 v[40:43], v[170:173], v[202:205], 0
	v_mfma_f32_16x16x32_bf16 v[32:35], v[142:145], v[210:213], 0
	v_mfma_f32_16x16x32_bf16 v[24:27], v[170:173], v[210:213], 0
	v_mfma_f32_16x16x32_bf16 v[16:19], v[142:145], v[218:221], 0
	v_mfma_f32_16x16x32_bf16 v[8:11], v[170:173], v[218:221], 0
	v_mfma_f32_16x16x32_bf16 v[64:67], v[166:169], v[198:201], v[64:67]
	v_mfma_f32_16x16x32_bf16 v[56:59], v[174:177], v[198:201], v[56:59]
	v_mfma_f32_16x16x32_bf16 v[48:51], v[166:169], v[206:209], v[48:51]
	v_mfma_f32_16x16x32_bf16 v[40:43], v[174:177], v[206:209], v[40:43]
	v_mfma_f32_16x16x32_bf16 v[32:35], v[166:169], v[214:217], v[32:35]
	v_mfma_f32_16x16x32_bf16 v[24:27], v[174:177], v[214:217], v[24:27]
	v_mfma_f32_16x16x32_bf16 v[16:19], v[166:169], v[222:225], v[16:19]
	v_mfma_f32_16x16x32_bf16 v[8:11], v[174:177], v[222:225], v[8:11]
	v_mfma_f32_16x16x32_bf16 v[60:63], v[178:181], v[194:197], 0
	v_mfma_f32_16x16x32_bf16 v[52:55], v[186:189], v[194:197], 0
	v_mfma_f32_16x16x32_bf16 v[44:47], v[178:181], v[202:205], 0
	v_mfma_f32_16x16x32_bf16 v[36:39], v[186:189], v[202:205], 0
	v_mfma_f32_16x16x32_bf16 v[28:31], v[178:181], v[210:213], 0
	v_mfma_f32_16x16x32_bf16 v[20:23], v[186:189], v[210:213], 0
	v_mfma_f32_16x16x32_bf16 v[12:15], v[178:181], v[218:221], 0
	v_mfma_f32_16x16x32_bf16 v[4:7], v[186:189], v[218:221], 0
	v_mfma_f32_16x16x32_bf16 v[60:63], v[182:185], v[198:201], v[60:63]
	v_mfma_f32_16x16x32_bf16 v[52:55], v[190:193], v[198:201], v[52:55]
	v_mfma_f32_16x16x32_bf16 v[44:47], v[182:185], v[206:209], v[44:47]
	v_mfma_f32_16x16x32_bf16 v[36:39], v[190:193], v[206:209], v[36:39]
	v_mfma_f32_16x16x32_bf16 v[28:31], v[182:185], v[214:217], v[28:31]
	v_mfma_f32_16x16x32_bf16 v[20:23], v[190:193], v[214:217], v[20:23]
	v_mfma_f32_16x16x32_bf16 v[12:15], v[182:185], v[222:225], v[12:15]
	v_mfma_f32_16x16x32_bf16 v[4:7], v[190:193], v[222:225], v[4:7]
	s_barrier
	s_add_i32 s52, 0, 0x18000
	v_add_u32_e32 v148, s52, v146
	s_add_i32 s53, 0, 0x1c000
	ds_read_b128 v[142:145], v148
	ds_read_b128 v[166:169], v148 offset:1024
	ds_read_b128 v[170:173], v148 offset:2048
	ds_read_b128 v[174:177], v148 offset:3072
	v_add_u32_e32 v148, s53, v146
	ds_read_b128 v[178:181], v148
	ds_read_b128 v[182:185], v148 offset:1024
	ds_read_b128 v[186:189], v148 offset:2048
	ds_read_b128 v[190:193], v148 offset:3072
	s_add_u32 s22, s22, 0x40000
	s_addc_u32 s23, s23, 0
	s_mov_b32 m0, s40
	v_lshl_add_u64 v[244:245], s[22:23], 0, v[136:137]
	ds_read_b128 v[194:197], v153 offset:32768
	ds_read_b128 v[198:201], v153 offset:33792
	ds_read_b128 v[202:205], v153 offset:34816
	ds_read_b128 v[206:209], v153 offset:35840
	ds_read_b128 v[210:213], v153 offset:36864
	ds_read_b128 v[214:217], v153 offset:37888
	ds_read_b128 v[218:221], v153 offset:38912
	ds_read_b128 v[222:225], v153 offset:39936
	global_load_lds_dwordx4 v[244:245], off
	v_lshl_add_u64 v[244:245], s[22:23], 0, v[132:133]
	s_mov_b32 m0, s41
	s_nop 0
	global_load_lds_dwordx4 v[244:245], off
	s_waitcnt vmcnt(8)
	s_waitcnt lgkmcnt(0)
	s_barrier
	s_waitcnt lgkmcnt(0)
	v_mfma_f32_16x16x32_bf16 v[128:131], v[142:145], v[194:197], v[128:131]
	v_mfma_f32_16x16x32_bf16 v[120:123], v[170:173], v[194:197], v[120:123]
	v_mfma_f32_16x16x32_bf16 v[112:115], v[142:145], v[202:205], v[112:115]
	v_mfma_f32_16x16x32_bf16 v[104:107], v[170:173], v[202:205], v[104:107]
	v_mfma_f32_16x16x32_bf16 v[96:99], v[142:145], v[210:213], v[96:99]
	v_mfma_f32_16x16x32_bf16 v[88:91], v[170:173], v[210:213], v[88:91]
	v_mfma_f32_16x16x32_bf16 v[80:83], v[142:145], v[218:221], v[80:83]
	v_mfma_f32_16x16x32_bf16 v[72:75], v[170:173], v[218:221], v[72:75]
	v_mfma_f32_16x16x32_bf16 v[128:131], v[166:169], v[198:201], v[128:131]
	v_mfma_f32_16x16x32_bf16 v[120:123], v[174:177], v[198:201], v[120:123]
	v_mfma_f32_16x16x32_bf16 v[112:115], v[166:169], v[206:209], v[112:115]
	v_mfma_f32_16x16x32_bf16 v[104:107], v[174:177], v[206:209], v[104:107]
	v_mfma_f32_16x16x32_bf16 v[96:99], v[166:169], v[214:217], v[96:99]
	v_mfma_f32_16x16x32_bf16 v[88:91], v[174:177], v[214:217], v[88:91]
	v_mfma_f32_16x16x32_bf16 v[80:83], v[166:169], v[222:225], v[80:83]
	v_mfma_f32_16x16x32_bf16 v[72:75], v[174:177], v[222:225], v[72:75]
	v_mfma_f32_16x16x32_bf16 v[124:127], v[178:181], v[194:197], v[124:127]
	v_mfma_f32_16x16x32_bf16 v[116:119], v[186:189], v[194:197], v[116:119]
	v_mfma_f32_16x16x32_bf16 v[108:111], v[178:181], v[202:205], v[108:111]
	v_mfma_f32_16x16x32_bf16 v[100:103], v[186:189], v[202:205], v[100:103]
	v_mfma_f32_16x16x32_bf16 v[92:95], v[178:181], v[210:213], v[92:95]
	v_mfma_f32_16x16x32_bf16 v[84:87], v[186:189], v[210:213], v[84:87]
	v_mfma_f32_16x16x32_bf16 v[76:79], v[178:181], v[218:221], v[76:79]
	v_mfma_f32_16x16x32_bf16 v[68:71], v[186:189], v[218:221], v[68:71]
	v_mfma_f32_16x16x32_bf16 v[124:127], v[182:185], v[198:201], v[124:127]
	v_mfma_f32_16x16x32_bf16 v[116:119], v[190:193], v[198:201], v[116:119]
	v_mfma_f32_16x16x32_bf16 v[108:111], v[182:185], v[206:209], v[108:111]
	v_mfma_f32_16x16x32_bf16 v[100:103], v[190:193], v[206:209], v[100:103]
	v_mfma_f32_16x16x32_bf16 v[92:95], v[182:185], v[214:217], v[92:95]
	v_mfma_f32_16x16x32_bf16 v[84:87], v[190:193], v[214:217], v[84:87]
	v_mfma_f32_16x16x32_bf16 v[76:79], v[182:185], v[222:225], v[76:79]
	v_mfma_f32_16x16x32_bf16 v[68:71], v[190:193], v[222:225], v[68:71]
	s_barrier
; #define PG8_STAGE(bufoff, gbase, voff) do { _Pragma("unroll") for (int _i = 0; _i < 2; ++_i) \
;         __builtin_amdgcn_global_load_lds((const unsigned*)((const char*)(gbase) + (voff)[_i]), (PG8_LAS unsigned*)(lds + (bufoff) + ldsw + _i * 8192), 16, 0, 0); } while (0)
; #define PG8_LDA(dst, b, h) do { _Pragma("unroll") for (int m = 0; m < 4; ++m) _Pragma("unroll") for (int k = 0; k < 2; ++k) dst[m][k] = *(const PG8_LAS bf16x8*)(lds + PG8_SA(b, h) + aoff + m * 2048 + k * 1024); } while (0)
; #define PG8_MMA(ai, bj, At, Bt) do { __builtin_amdgcn_s_setprio(1); _Pragma("unroll") for (int m = 0; m < 4; ++m) _Pragma("unroll") for (int n = 0; n < 2; ++n) _Pragma("unroll") for (int k = 0; k < 2; ++k) \
;         acc[ai][bj][m][n] = __builtin_amdgcn_mfma_f32_16x16x32_bf16(Bt[n][k], At[m][k], acc[ai][bj][m][n], 0, 0, 0); __builtin_amdgcn_s_setprio(0); } while (0)
; #define PG8_WAIT_V(n) asm volatile("s_waitcnt vmcnt(" #n ")" ::: "memory")
; #define PG8_WAIT_L(n) asm volatile("s_waitcnt lgkmcnt(" #n ")" ::: "memory")
; #define PG8_BAR __builtin_amdgcn_s_barrier()
; #define PG8_SCHED __builtin_amdgcn_sched_barrier(0)
; template <class Epi, class Sched, bool ALIGN_EPI = false, bool SP2 = false>
; __device__ __forceinline__ void gemm_phase(PG8_LAS unsigned char* lds, const Gemm g, const Sched& S, const Epi& E, const int tid) {
;     ...
;             PG8_LDA(At, 1, 1); PG8_STAGE(PG8_SB(1, 0), b3, voffB); PG8_STAGE(PG8_SB(1, 1), b3 + hstep, voffB); PG8_STAGE(PG8_SA(1, 0), a3, voffA);
;             PG8_WAIT_V(8); PG8_WAIT_L(0); PG8_BAR; PG8_MMA(1, 0, At, B0); PG8_MMA(1, 1, At, B1); PG8_BAR; PG8_SCHED;
	s_add_i32 s22, s52, s37
	v_lshl_add_u64 v[226:227], v[226:227], 0, s[0:1]
	s_mov_b32 m0, s22
	ds_read_b128 v[194:197], v153 offset:49152
	ds_read_b128 v[198:201], v153 offset:50176
	ds_read_b128 v[202:205], v153 offset:51200
	ds_read_b128 v[206:209], v153 offset:52224
	ds_read_b128 v[210:213], v153 offset:53248
	ds_read_b128 v[214:217], v153 offset:54272
	ds_read_b128 v[218:221], v153 offset:55296
	ds_read_b128 v[222:225], v153 offset:56320
	global_load_lds_dwordx4 v[226:227], off
	s_add_i32 m0, s22, 0x2000
	s_add_u32 s20, s20, 0x40080
	v_lshl_add_u64 v[226:227], v[238:239], 0, s[0:1]
	s_addc_u32 s21, s21, 0
	s_add_i32 s22, s53, s37
	global_load_lds_dwordx4 v[226:227], off
	v_lshl_add_u64 v[226:227], s[20:21], 0, v[134:135]
	s_mov_b32 m0, s22
	s_nop 0
	global_load_lds_dwordx4 v[226:227], off
	v_lshl_add_u64 v[226:227], s[20:21], 0, v[0:1]
	s_add_i32 m0, s22, 0x2000
	s_nop 0
	global_load_lds_dwordx4 v[226:227], off
	v_lshl_add_u64 v[226:227], v[240:241], 0, s[0:1]
	s_mov_b32 m0, s42
	s_nop 0
	global_load_lds_dwordx4 v[226:227], off
	v_lshl_add_u64 v[226:227], v[242:243], 0, s[0:1]
	s_mov_b32 m0, s43
	s_nop 0
	global_load_lds_dwordx4 v[226:227], off
	s_waitcnt vmcnt(8)
	s_waitcnt lgkmcnt(0)
	s_barrier
	s_waitcnt lgkmcnt(0)
	v_mfma_f32_16x16x32_bf16 v[64:67], v[142:145], v[194:197], v[64:67]
	v_mfma_f32_16x16x32_bf16 v[56:59], v[170:173], v[194:197], v[56:59]
	v_mfma_f32_16x16x32_bf16 v[48:51], v[142:145], v[202:205], v[48:51]
	v_mfma_f32_16x16x32_bf16 v[40:43], v[170:173], v[202:205], v[40:43]
	v_mfma_f32_16x16x32_bf16 v[32:35], v[142:145], v[210:213], v[32:35]
	v_mfma_f32_16x16x32_bf16 v[24:27], v[170:173], v[210:213], v[24:27]
	v_mfma_f32_16x16x32_bf16 v[16:19], v[142:145], v[218:221], v[16:19]
	v_mfma_f32_16x16x32_bf16 v[8:11], v[170:173], v[218:221], v[8:11]
	v_mfma_f32_16x16x32_bf16 v[64:67], v[166:169], v[198:201], v[64:67]
	v_mfma_f32_16x16x32_bf16 v[56:59], v[174:177], v[198:201], v[56:59]
	v_mfma_f32_16x16x32_bf16 v[48:51], v[166:169], v[206:209], v[48:51]
	v_mfma_f32_16x16x32_bf16 v[40:43], v[174:177], v[206:209], v[40:43]
	v_mfma_f32_16x16x32_bf16 v[32:35], v[166:169], v[214:217], v[32:35]
	v_mfma_f32_16x16x32_bf16 v[24:27], v[174:177], v[214:217], v[24:27]
	v_mfma_f32_16x16x32_bf16 v[16:19], v[166:169], v[222:225], v[16:19]
	v_mfma_f32_16x16x32_bf16 v[8:11], v[174:177], v[222:225], v[8:11]
	v_mfma_f32_16x16x32_bf16 v[60:63], v[178:181], v[194:197], v[60:63]
	v_mfma_f32_16x16x32_bf16 v[52:55], v[186:189], v[194:197], v[52:55]
	v_mfma_f32_16x16x32_bf16 v[44:47], v[178:181], v[202:205], v[44:47]
	v_mfma_f32_16x16x32_bf16 v[36:39], v[186:189], v[202:205], v[36:39]
	v_mfma_f32_16x16x32_bf16 v[28:31], v[178:181], v[210:213], v[28:31]
	v_mfma_f32_16x16x32_bf16 v[20:23], v[186:189], v[210:213], v[20:23]
	v_mfma_f32_16x16x32_bf16 v[12:15], v[178:181], v[218:221], v[12:15]
	v_mfma_f32_16x16x32_bf16 v[4:7], v[186:189], v[218:221], v[4:7]
	v_mfma_f32_16x16x32_bf16 v[60:63], v[182:185], v[198:201], v[60:63]
	v_mfma_f32_16x16x32_bf16 v[52:55], v[190:193], v[198:201], v[52:55]
	v_mfma_f32_16x16x32_bf16 v[44:47], v[182:185], v[206:209], v[44:47]
	v_mfma_f32_16x16x32_bf16 v[36:39], v[190:193], v[206:209], v[36:39]
	v_mfma_f32_16x16x32_bf16 v[28:31], v[182:185], v[214:217], v[28:31]
	v_mfma_f32_16x16x32_bf16 v[20:23], v[190:193], v[214:217], v[20:23]
	v_mfma_f32_16x16x32_bf16 v[12:15], v[182:185], v[222:225], v[12:15]
	v_mfma_f32_16x16x32_bf16 v[4:7], v[190:193], v[222:225], v[4:7]
	s_barrier
	s_add_i32 s51, s51, 2
	s_add_u32 s18, s18, 0x100
	s_addc_u32 s19, s19, 0
	s_add_u32 s49, s49, 0x100
	s_addc_u32 s50, s50, 0
	s_cmp_gt_u32 s51, 13
	s_cbranch_scc0 .LBB0_522
	s_branch .Lpeel_exit3

; #define PG8_STAGE(bufoff, gbase, voff) do { _Pragma("unroll") for (int _i = 0; _i < 2; ++_i) \
;         __builtin_amdgcn_global_load_lds((const unsigned*)((const char*)(gbase) + (voff)[_i]), (PG8_LAS unsigned*)(lds + (bufoff) + ldsw + _i * 8192), 16, 0, 0); } while (0)
; #define PG8_LDA(dst, b, h) do { _Pragma("unroll") for (int m = 0; m < 4; ++m) _Pragma("unroll") for (int k = 0; k < 2; ++k) dst[m][k] = *(const PG8_LAS bf16x8*)(lds + PG8_SA(b, h) + aoff + m * 2048 + k * 1024); } while (0)
; #define PG8_LDB(dst, b, h) do { _Pragma("unroll") for (int n = 0; n < 2; ++n) _Pragma("unroll") for (int k = 0; k < 2; ++k) dst[n][k] = *(const PG8_LAS bf16x8*)(lds + PG8_SB(b, h) + boff + n * 2048 + k * 1024); } while (0)
; #define PG8_WAIT_V(n) asm volatile("s_waitcnt vmcnt(" #n ")" ::: "memory")
; #define PG8_WAIT_L(n) asm volatile("s_waitcnt lgkmcnt(" #n ")" ::: "memory")
; #define PG8_BAR __builtin_amdgcn_s_barrier()
; #define PG8_SCHED __builtin_amdgcn_sched_barrier(0)
; template <class Epi, class Sched, bool ALIGN_EPI = false, bool SP2 = false>
; __device__ __forceinline__ void gemm_phase(PG8_LAS unsigned char* lds, const Gemm g, const Sched& S, const Epi& E, const int tid) {
;     ...
;         const bool has_next = S.next(ui + 1, nxt);
;         const char* nA = has_next ? (const char*)g.A + (size_t)nxt.pm * tstep : cA; const char* nB = has_next ? (const char*)g.Bt + (size_t)nxt.pn * tstep : cB;
;         for (int t = 0; t < nt; t += 2) {
;             const bool last = (t == nt - 2);
;             const char* a1 = cA + (size_t)(t + 1) * kstep;
;             const char* a2 = last ? nA : cA + (size_t)(t + 2) * kstep; const char* b2 = last ? nB : cB + (size_t)(t + 2) * kstep;
;             const char* a3 = a2 + kstep; const char* b3 = b2 + kstep;
;             if (last && has_next) S.a_ready(nxt);
;             if constexpr (SP2) {
;             PG8_LDB(B0, 0, 0); PG8_LDB(B1, 0, 1); PG8_SCHED; PG8_LDA(At, 0, 0); PG8_STAGE(PG8_SA(1, 1), a1 + hstep, voffA);
;             PG8_WAIT_V(8); PG8_WAIT_L(0); PG8_BAR; PG8_MMA(0, 0, At, B0); PG8_MMA(0, 1, At, B1); PG8_BAR; PG8_SCHED;
;             PG8_LDA(At, 0, 1); PG8_STAGE(PG8_SB(0, 0), b2, voffB); PG8_STAGE(PG8_SB(0, 1), b2 + hstep, voffB); PG8_STAGE(PG8_SA(0, 0), a2, voffA);
;             PG8_WAIT_V(8); PG8_WAIT_L(0); PG8_BAR; PG8_MMA(1, 0, At, B0); PG8_MMA(1, 1, At, B1); PG8_BAR; PG8_SCHED;
.LBB0_841:
	s_ashr_i32 s13, s12, 31
	s_lshl_b64 s[14:15], s[12:13], 19
	s_add_u32 s14, s34, s14
	s_addc_u32 s15, s36, s15
	s_and_b64 s[16:17], s[38:39], exec
	s_cselect_b32 s13, s15, s23
	s_cselect_b32 s19, s14, s22
	s_ashr_i32 s11, s10, 31
	s_lshl_b64 s[16:17], s[10:11], 19
	s_add_u32 s16, s4, s16
	s_addc_u32 s17, s5, s17
	s_and_b64 s[26:27], s[38:39], exec
	s_cselect_b32 s11, s17, s25
	s_cselect_b32 s46, s16, s24
	s_add_u32 s22, s22, 0x40080
	s_addc_u32 s23, s23, 0
	s_add_u32 s47, s24, 0x100
	v_mov_b32_e32 v4, 0
	s_addc_u32 s48, s25, 0
	s_mov_b32 s49, -2
	s_add_u32 s24, s22, 0xfffc0080
	s_addc_u32 s25, s23, -1
	s_add_i32 s50, 0, 0x10000
	s_cmp_eq_u32 s49, 12
	s_cselect_b32 s27, s13, s25
	s_cselect_b32 s26, s19, s24
	v_add_u32_e32 v148, s50, v146
	s_cselect_b32 s25, s11, s48
	s_cselect_b32 s24, s46, s47
	s_add_i32 s52, 0, 0x14000
	ds_read_b128 v[142:145], v148
	ds_read_b128 v[166:169], v148 offset:1024
	ds_read_b128 v[170:173], v148 offset:2048
	ds_read_b128 v[174:177], v148 offset:3072
	v_add_u32_e32 v148, s52, v146
	ds_read_b128 v[178:181], v148
	ds_read_b128 v[182:185], v148 offset:1024
	ds_read_b128 v[186:189], v148 offset:2048
	ds_read_b128 v[190:193], v148 offset:3072
	v_lshl_add_u64 v[226:227], s[22:23], 0, v[138:139]
	s_add_i32 m0, s21, 0xc000
	ds_read_b128 v[194:197], v153
	ds_read_b128 v[198:201], v153 offset:1024
	ds_read_b128 v[202:205], v153 offset:2048
	ds_read_b128 v[206:209], v153 offset:3072
	ds_read_b128 v[210:213], v153 offset:4096
	ds_read_b128 v[214:217], v153 offset:5120
	ds_read_b128 v[218:221], v153 offset:6144
	ds_read_b128 v[222:225], v153 offset:7168
	global_load_lds_dwordx4 v[226:227], off
	v_lshl_add_u64 v[226:227], s[22:23], 0, v[140:141]
	s_add_i32 m0, s21, 0xe000
	s_nop 0
	global_load_lds_dwordx4 v[226:227], off
	s_waitcnt vmcnt(8)
	s_waitcnt lgkmcnt(0)
	s_barrier
	s_waitcnt lgkmcnt(0)
	v_mfma_f32_16x16x32_bf16 v[128:131], v[142:145], v[194:197], 0
	v_mfma_f32_16x16x32_bf16 v[124:127], v[170:173], v[194:197], 0
	v_mfma_f32_16x16x32_bf16 v[112:115], v[142:145], v[202:205], 0
	v_mfma_f32_16x16x32_bf16 v[108:111], v[170:173], v[202:205], 0
	v_mfma_f32_16x16x32_bf16 v[96:99], v[142:145], v[210:213], 0
	v_mfma_f32_16x16x32_bf16 v[92:95], v[170:173], v[210:213], 0
	v_mfma_f32_16x16x32_bf16 v[80:83], v[142:145], v[218:221], 0
	v_mfma_f32_16x16x32_bf16 v[76:79], v[170:173], v[218:221], 0
	v_mfma_f32_16x16x32_bf16 v[128:131], v[166:169], v[198:201], v[128:131]
	v_mfma_f32_16x16x32_bf16 v[124:127], v[174:177], v[198:201], v[124:127]
	v_mfma_f32_16x16x32_bf16 v[112:115], v[166:169], v[206:209], v[112:115]
	v_mfma_f32_16x16x32_bf16 v[108:111], v[174:177], v[206:209], v[108:111]
	v_mfma_f32_16x16x32_bf16 v[96:99], v[166:169], v[214:217], v[96:99]
	v_mfma_f32_16x16x32_bf16 v[92:95], v[174:177], v[214:217], v[92:95]
	v_mfma_f32_16x16x32_bf16 v[80:83], v[166:169], v[222:225], v[80:83]
	v_mfma_f32_16x16x32_bf16 v[76:79], v[174:177], v[222:225], v[76:79]
	v_mfma_f32_16x16x32_bf16 v[120:123], v[178:181], v[194:197], 0
	v_mfma_f32_16x16x32_bf16 v[116:119], v[186:189], v[194:197], 0
	v_mfma_f32_16x16x32_bf16 v[104:107], v[178:181], v[202:205], 0
	v_mfma_f32_16x16x32_bf16 v[100:103], v[186:189], v[202:205], 0
	v_mfma_f32_16x16x32_bf16 v[88:91], v[178:181], v[210:213], 0
	v_mfma_f32_16x16x32_bf16 v[84:87], v[186:189], v[210:213], 0
	v_mfma_f32_16x16x32_bf16 v[72:75], v[178:181], v[218:221], 0
	v_mfma_f32_16x16x32_bf16 v[68:71], v[186:189], v[218:221], 0
	v_mfma_f32_16x16x32_bf16 v[120:123], v[182:185], v[198:201], v[120:123]
	v_mfma_f32_16x16x32_bf16 v[116:119], v[190:193], v[198:201], v[116:119]
	v_mfma_f32_16x16x32_bf16 v[104:107], v[182:185], v[206:209], v[104:107]
	v_mfma_f32_16x16x32_bf16 v[100:103], v[190:193], v[206:209], v[100:103]
	v_mfma_f32_16x16x32_bf16 v[88:91], v[182:185], v[214:217], v[88:91]
	v_mfma_f32_16x16x32_bf16 v[84:87], v[190:193], v[214:217], v[84:87]
	v_mfma_f32_16x16x32_bf16 v[72:75], v[182:185], v[222:225], v[72:75]
	v_mfma_f32_16x16x32_bf16 v[68:71], v[190:193], v[222:225], v[68:71]
	s_barrier
	s_add_i32 s50, s50, s37
	v_lshl_add_u64 v[226:227], s[24:25], 0, v[132:133]
	s_mov_b32 m0, s50
	ds_read_b128 v[194:197], v153 offset:16384
	ds_read_b128 v[198:201], v153 offset:17408
	ds_read_b128 v[202:205], v153 offset:18432
	ds_read_b128 v[206:209], v153 offset:19456
	ds_read_b128 v[210:213], v153 offset:20480
	ds_read_b128 v[214:217], v153 offset:21504
	ds_read_b128 v[218:221], v153 offset:22528
	ds_read_b128 v[222:225], v153 offset:23552
	global_load_lds_dwordx4 v[226:227], off
	s_add_i32 m0, s50, 0x2000
	s_add_u32 s50, s24, 0x40000
	v_lshl_add_u64 v[238:239], s[24:25], 0, v[136:137]
	s_addc_u32 s51, s25, 0
	s_add_i32 s52, s52, s37
	global_load_lds_dwordx4 v[238:239], off
	v_lshl_add_u64 v[240:241], s[50:51], 0, v[132:133]
	s_mov_b32 m0, s52
	v_lshl_add_u64 v[242:243], s[26:27], 0, v[134:135]
	global_load_lds_dwordx4 v[240:241], off
	v_lshl_add_u64 v[240:241], s[50:51], 0, v[136:137]
	s_add_i32 m0, s52, 0x2000
	s_nop 0
	global_load_lds_dwordx4 v[240:241], off
	v_lshl_add_u64 v[240:241], s[26:27], 0, v[0:1]
	s_mov_b32 m0, s21
	s_nop 0
	global_load_lds_dwordx4 v[240:241], off
	s_mov_b32 m0, s40
	s_nop 0
	global_load_lds_dwordx4 v[242:243], off
	s_waitcnt vmcnt(8)
	s_waitcnt lgkmcnt(0)
	s_barrier
; #define PG8_STAGE(bufoff, gbase, voff) do { _Pragma("unroll") for (int _i = 0; _i < 2; ++_i) \
;         __builtin_amdgcn_global_load_lds((const unsigned*)((const char*)(gbase) + (voff)[_i]), (PG8_LAS unsigned*)(lds + (bufoff) + ldsw + _i * 8192), 16, 0, 0); } while (0)
; #define PG8_LDA(dst, b, h) do { _Pragma("unroll") for (int m = 0; m < 4; ++m) _Pragma("unroll") for (int k = 0; k < 2; ++k) dst[m][k] = *(const PG8_LAS bf16x8*)(lds + PG8_SA(b, h) + aoff + m * 2048 + k * 1024); } while (0)
; #define PG8_LDB(dst, b, h) do { _Pragma("unroll") for (int n = 0; n < 2; ++n) _Pragma("unroll") for (int k = 0; k < 2; ++k) dst[n][k] = *(const PG8_LAS bf16x8*)(lds + PG8_SB(b, h) + boff + n * 2048 + k * 1024); } while (0)
; #define PG8_MMA(ai, bj, At, Bt) do { __builtin_amdgcn_s_setprio(1); _Pragma("unroll") for (int m = 0; m < 4; ++m) _Pragma("unroll") for (int n = 0; n < 2; ++n) _Pragma("unroll") for (int k = 0; k < 2; ++k) \
;         acc[ai][bj][m][n] = __builtin_amdgcn_mfma_f32_16x16x32_bf16(Bt[n][k], At[m][k], acc[ai][bj][m][n], 0, 0, 0); __builtin_amdgcn_s_setprio(0); } while (0)
; #define PG8_WAIT_V(n) asm volatile("s_waitcnt vmcnt(" #n ")" ::: "memory")
; #define PG8_WAIT_L(n) asm volatile("s_waitcnt lgkmcnt(" #n ")" ::: "memory")
; #define PG8_BAR __builtin_amdgcn_s_barrier()
; #define PG8_SCHED __builtin_amdgcn_sched_barrier(0)
; template <class Epi, class Sched, bool ALIGN_EPI = false, bool SP2 = false>
; __device__ __forceinline__ void gemm_phase(PG8_LAS unsigned char* lds, const Gemm g, const Sched& S, const Epi& E, const int tid) {
;     ...
;             PG8_WAIT_V(8); PG8_WAIT_L(0); PG8_BAR; PG8_MMA(1, 0, At, B0); PG8_MMA(1, 1, At, B1); PG8_BAR; PG8_SCHED;
;             PG8_LDB(B0, 1, 0); PG8_LDB(B1, 1, 1); PG8_SCHED; PG8_LDA(At, 1, 0); PG8_STAGE(PG8_SA(0, 1), a2 + hstep, voffA);
;             PG8_WAIT_V(8); PG8_WAIT_L(0); PG8_BAR; PG8_MMA(0, 0, At, B0); PG8_MMA(0, 1, At, B1); PG8_BAR; PG8_SCHED;
;             PG8_LDA(At, 1, 1); PG8_STAGE(PG8_SB(1, 0), b3, voffB); PG8_STAGE(PG8_SB(1, 1), b3 + hstep, voffB); PG8_STAGE(PG8_SA(1, 0), a3, voffA);
	s_waitcnt lgkmcnt(0)
	v_mfma_f32_16x16x32_bf16 v[64:67], v[142:145], v[194:197], 0
	v_mfma_f32_16x16x32_bf16 v[60:63], v[170:173], v[194:197], 0
	v_mfma_f32_16x16x32_bf16 v[48:51], v[142:145], v[202:205], 0
	v_mfma_f32_16x16x32_bf16 v[44:47], v[170:173], v[202:205], 0
	v_mfma_f32_16x16x32_bf16 v[32:35], v[142:145], v[210:213], 0
	v_mfma_f32_16x16x32_bf16 v[28:31], v[170:173], v[210:213], 0
	v_mfma_f32_16x16x32_bf16 v[16:19], v[142:145], v[218:221], 0
	v_mfma_f32_16x16x32_bf16 v[12:15], v[170:173], v[218:221], 0
	v_mfma_f32_16x16x32_bf16 v[64:67], v[166:169], v[198:201], v[64:67]
	v_mfma_f32_16x16x32_bf16 v[60:63], v[174:177], v[198:201], v[60:63]
	v_mfma_f32_16x16x32_bf16 v[48:51], v[166:169], v[206:209], v[48:51]
	v_mfma_f32_16x16x32_bf16 v[44:47], v[174:177], v[206:209], v[44:47]
	v_mfma_f32_16x16x32_bf16 v[32:35], v[166:169], v[214:217], v[32:35]
	v_mfma_f32_16x16x32_bf16 v[28:31], v[174:177], v[214:217], v[28:31]
	v_mfma_f32_16x16x32_bf16 v[16:19], v[166:169], v[222:225], v[16:19]
	v_mfma_f32_16x16x32_bf16 v[12:15], v[174:177], v[222:225], v[12:15]
	v_mfma_f32_16x16x32_bf16 v[56:59], v[178:181], v[194:197], 0
	v_mfma_f32_16x16x32_bf16 v[52:55], v[186:189], v[194:197], 0
	v_mfma_f32_16x16x32_bf16 v[40:43], v[178:181], v[202:205], 0
	v_mfma_f32_16x16x32_bf16 v[36:39], v[186:189], v[202:205], 0
	v_mfma_f32_16x16x32_bf16 v[24:27], v[178:181], v[210:213], 0
	v_mfma_f32_16x16x32_bf16 v[20:23], v[186:189], v[210:213], 0
	v_mfma_f32_16x16x32_bf16 v[8:11], v[178:181], v[218:221], 0
	v_mfma_f32_16x16x32_bf16 v[4:7], v[186:189], v[218:221], 0
	v_mfma_f32_16x16x32_bf16 v[56:59], v[182:185], v[198:201], v[56:59]
	v_mfma_f32_16x16x32_bf16 v[52:55], v[190:193], v[198:201], v[52:55]
	v_mfma_f32_16x16x32_bf16 v[40:43], v[182:185], v[206:209], v[40:43]
	v_mfma_f32_16x16x32_bf16 v[36:39], v[190:193], v[206:209], v[36:39]
	v_mfma_f32_16x16x32_bf16 v[24:27], v[182:185], v[214:217], v[24:27]
	v_mfma_f32_16x16x32_bf16 v[20:23], v[190:193], v[214:217], v[20:23]
	v_mfma_f32_16x16x32_bf16 v[8:11], v[182:185], v[222:225], v[8:11]
	v_mfma_f32_16x16x32_bf16 v[4:7], v[190:193], v[222:225], v[4:7]
	s_barrier
	s_add_i32 s50, 0, 0x18000
	v_add_u32_e32 v148, s50, v146
	s_add_i32 s51, 0, 0x1c000
	ds_read_b128 v[142:145], v148
	ds_read_b128 v[166:169], v148 offset:1024
	ds_read_b128 v[170:173], v148 offset:2048
	ds_read_b128 v[174:177], v148 offset:3072
	v_add_u32_e32 v148, s51, v146
	ds_read_b128 v[178:181], v148
	ds_read_b128 v[182:185], v148 offset:1024
	ds_read_b128 v[186:189], v148 offset:2048
	ds_read_b128 v[190:193], v148 offset:3072
	s_add_u32 s26, s26, 0x40000
	s_addc_u32 s27, s27, 0
	s_mov_b32 m0, s41
	v_lshl_add_u64 v[244:245], s[26:27], 0, v[0:1]
	ds_read_b128 v[194:197], v153 offset:32768
	ds_read_b128 v[198:201], v153 offset:33792
	ds_read_b128 v[202:205], v153 offset:34816
	ds_read_b128 v[206:209], v153 offset:35840
	ds_read_b128 v[210:213], v153 offset:36864
	ds_read_b128 v[214:217], v153 offset:37888
	ds_read_b128 v[218:221], v153 offset:38912
	ds_read_b128 v[222:225], v153 offset:39936
	global_load_lds_dwordx4 v[244:245], off
	v_lshl_add_u64 v[244:245], s[26:27], 0, v[134:135]
	s_mov_b32 m0, s42
	s_nop 0
	global_load_lds_dwordx4 v[244:245], off
	s_waitcnt vmcnt(8)
	s_waitcnt lgkmcnt(0)
	s_barrier
	s_waitcnt lgkmcnt(0)
	v_mfma_f32_16x16x32_bf16 v[128:131], v[142:145], v[194:197], v[128:131]
	v_mfma_f32_16x16x32_bf16 v[124:127], v[170:173], v[194:197], v[124:127]
	v_mfma_f32_16x16x32_bf16 v[112:115], v[142:145], v[202:205], v[112:115]
	v_mfma_f32_16x16x32_bf16 v[108:111], v[170:173], v[202:205], v[108:111]
	v_mfma_f32_16x16x32_bf16 v[96:99], v[142:145], v[210:213], v[96:99]
	v_mfma_f32_16x16x32_bf16 v[92:95], v[170:173], v[210:213], v[92:95]
	v_mfma_f32_16x16x32_bf16 v[80:83], v[142:145], v[218:221], v[80:83]
	v_mfma_f32_16x16x32_bf16 v[76:79], v[170:173], v[218:221], v[76:79]
	v_mfma_f32_16x16x32_bf16 v[128:131], v[166:169], v[198:201], v[128:131]
	v_mfma_f32_16x16x32_bf16 v[124:127], v[174:177], v[198:201], v[124:127]
	v_mfma_f32_16x16x32_bf16 v[112:115], v[166:169], v[206:209], v[112:115]
	v_mfma_f32_16x16x32_bf16 v[108:111], v[174:177], v[206:209], v[108:111]
	v_mfma_f32_16x16x32_bf16 v[96:99], v[166:169], v[214:217], v[96:99]
	v_mfma_f32_16x16x32_bf16 v[92:95], v[174:177], v[214:217], v[92:95]
	v_mfma_f32_16x16x32_bf16 v[80:83], v[166:169], v[222:225], v[80:83]
	v_mfma_f32_16x16x32_bf16 v[76:79], v[174:177], v[222:225], v[76:79]
	v_mfma_f32_16x16x32_bf16 v[120:123], v[178:181], v[194:197], v[120:123]
	v_mfma_f32_16x16x32_bf16 v[116:119], v[186:189], v[194:197], v[116:119]
	v_mfma_f32_16x16x32_bf16 v[104:107], v[178:181], v[202:205], v[104:107]
	v_mfma_f32_16x16x32_bf16 v[100:103], v[186:189], v[202:205], v[100:103]
	v_mfma_f32_16x16x32_bf16 v[88:91], v[178:181], v[210:213], v[88:91]
	v_mfma_f32_16x16x32_bf16 v[84:87], v[186:189], v[210:213], v[84:87]
	v_mfma_f32_16x16x32_bf16 v[72:75], v[178:181], v[218:221], v[72:75]
	v_mfma_f32_16x16x32_bf16 v[68:71], v[186:189], v[218:221], v[68:71]
	v_mfma_f32_16x16x32_bf16 v[120:123], v[182:185], v[198:201], v[120:123]
	v_mfma_f32_16x16x32_bf16 v[116:119], v[190:193], v[198:201], v[116:119]
	v_mfma_f32_16x16x32_bf16 v[104:107], v[182:185], v[206:209], v[104:107]
	v_mfma_f32_16x16x32_bf16 v[100:103], v[190:193], v[206:209], v[100:103]
	v_mfma_f32_16x16x32_bf16 v[88:91], v[182:185], v[214:217], v[88:91]
	v_mfma_f32_16x16x32_bf16 v[84:87], v[190:193], v[214:217], v[84:87]
	v_mfma_f32_16x16x32_bf16 v[72:75], v[182:185], v[222:225], v[72:75]
	v_mfma_f32_16x16x32_bf16 v[68:71], v[190:193], v[222:225], v[68:71]
	s_barrier
; #define PG8_STAGE(bufoff, gbase, voff) do { _Pragma("unroll") for (int _i = 0; _i < 2; ++_i) \
;         __builtin_amdgcn_global_load_lds((const unsigned*)((const char*)(gbase) + (voff)[_i]), (PG8_LAS unsigned*)(lds + (bufoff) + ldsw + _i * 8192), 16, 0, 0); } while (0)
; #define PG8_LDA(dst, b, h) do { _Pragma("unroll") for (int m = 0; m < 4; ++m) _Pragma("unroll") for (int k = 0; k < 2; ++k) dst[m][k] = *(const PG8_LAS bf16x8*)(lds + PG8_SA(b, h) + aoff + m * 2048 + k * 1024); } while (0)
; #define PG8_MMA(ai, bj, At, Bt) do { __builtin_amdgcn_s_setprio(1); _Pragma("unroll") for (int m = 0; m < 4; ++m) _Pragma("unroll") for (int n = 0; n < 2; ++n) _Pragma("unroll") for (int k = 0; k < 2; ++k) \
;         acc[ai][bj][m][n] = __builtin_amdgcn_mfma_f32_16x16x32_bf16(Bt[n][k], At[m][k], acc[ai][bj][m][n], 0, 0, 0); __builtin_amdgcn_s_setprio(0); } while (0)
; #define PG8_WAIT_V(n) asm volatile("s_waitcnt vmcnt(" #n ")" ::: "memory")
; #define PG8_WAIT_L(n) asm volatile("s_waitcnt lgkmcnt(" #n ")" ::: "memory")
; #define PG8_BAR __builtin_amdgcn_s_barrier()
; #define PG8_SCHED __builtin_amdgcn_sched_barrier(0)
; template <class Epi, class Sched, bool ALIGN_EPI = false, bool SP2 = false>
; __device__ __forceinline__ void gemm_phase(PG8_LAS unsigned char* lds, const Gemm g, const Sched& S, const Epi& E, const int tid) {
;     ...
;             PG8_LDA(At, 1, 1); PG8_STAGE(PG8_SB(1, 0), b3, voffB); PG8_STAGE(PG8_SB(1, 1), b3 + hstep, voffB); PG8_STAGE(PG8_SA(1, 0), a3, voffA);
;             PG8_WAIT_V(8); PG8_WAIT_L(0); PG8_BAR; PG8_MMA(1, 0, At, B0); PG8_MMA(1, 1, At, B1); PG8_BAR; PG8_SCHED;
	s_add_i32 s26, s50, s37
	v_lshl_add_u64 v[226:227], v[226:227], 0, s[0:1]
	s_mov_b32 m0, s26
	ds_read_b128 v[194:197], v153 offset:49152
	ds_read_b128 v[198:201], v153 offset:50176
	ds_read_b128 v[202:205], v153 offset:51200
	ds_read_b128 v[206:209], v153 offset:52224
	ds_read_b128 v[210:213], v153 offset:53248
	ds_read_b128 v[214:217], v153 offset:54272
	ds_read_b128 v[218:221], v153 offset:55296
	ds_read_b128 v[222:225], v153 offset:56320
	global_load_lds_dwordx4 v[226:227], off
	s_add_i32 m0, s26, 0x2000
	s_add_u32 s24, s24, 0x40080
	v_lshl_add_u64 v[226:227], v[238:239], 0, s[0:1]
	s_addc_u32 s25, s25, 0
	s_add_i32 s26, s51, s37
	global_load_lds_dwordx4 v[226:227], off
	v_lshl_add_u64 v[226:227], s[24:25], 0, v[132:133]
	s_mov_b32 m0, s26
	s_nop 0
	global_load_lds_dwordx4 v[226:227], off
	v_lshl_add_u64 v[226:227], s[24:25], 0, v[136:137]
	s_add_i32 m0, s26, 0x2000
	s_nop 0
	global_load_lds_dwordx4 v[226:227], off
	v_lshl_add_u64 v[226:227], v[240:241], 0, s[0:1]
	s_mov_b32 m0, s43
	s_nop 0
	global_load_lds_dwordx4 v[226:227], off
	v_lshl_add_u64 v[226:227], v[242:243], 0, s[0:1]
	s_mov_b32 m0, s44
	s_nop 0
	global_load_lds_dwordx4 v[226:227], off
	s_waitcnt vmcnt(8)
	s_waitcnt lgkmcnt(0)
	s_barrier
	s_waitcnt lgkmcnt(0)
	v_mfma_f32_16x16x32_bf16 v[64:67], v[142:145], v[194:197], v[64:67]
	v_mfma_f32_16x16x32_bf16 v[60:63], v[170:173], v[194:197], v[60:63]
	v_mfma_f32_16x16x32_bf16 v[48:51], v[142:145], v[202:205], v[48:51]
	v_mfma_f32_16x16x32_bf16 v[44:47], v[170:173], v[202:205], v[44:47]
	v_mfma_f32_16x16x32_bf16 v[32:35], v[142:145], v[210:213], v[32:35]
	v_mfma_f32_16x16x32_bf16 v[28:31], v[170:173], v[210:213], v[28:31]
	v_mfma_f32_16x16x32_bf16 v[16:19], v[142:145], v[218:221], v[16:19]
	v_mfma_f32_16x16x32_bf16 v[12:15], v[170:173], v[218:221], v[12:15]
	v_mfma_f32_16x16x32_bf16 v[64:67], v[166:169], v[198:201], v[64:67]
	v_mfma_f32_16x16x32_bf16 v[60:63], v[174:177], v[198:201], v[60:63]
	v_mfma_f32_16x16x32_bf16 v[48:51], v[166:169], v[206:209], v[48:51]
	v_mfma_f32_16x16x32_bf16 v[44:47], v[174:177], v[206:209], v[44:47]
	v_mfma_f32_16x16x32_bf16 v[32:35], v[166:169], v[214:217], v[32:35]
	v_mfma_f32_16x16x32_bf16 v[28:31], v[174:177], v[214:217], v[28:31]
	v_mfma_f32_16x16x32_bf16 v[16:19], v[166:169], v[222:225], v[16:19]
	v_mfma_f32_16x16x32_bf16 v[12:15], v[174:177], v[222:225], v[12:15]
	v_mfma_f32_16x16x32_bf16 v[56:59], v[178:181], v[194:197], v[56:59]
	v_mfma_f32_16x16x32_bf16 v[52:55], v[186:189], v[194:197], v[52:55]
	v_mfma_f32_16x16x32_bf16 v[40:43], v[178:181], v[202:205], v[40:43]
	v_mfma_f32_16x16x32_bf16 v[36:39], v[186:189], v[202:205], v[36:39]
	v_mfma_f32_16x16x32_bf16 v[24:27], v[178:181], v[210:213], v[24:27]
	v_mfma_f32_16x16x32_bf16 v[20:23], v[186:189], v[210:213], v[20:23]
	v_mfma_f32_16x16x32_bf16 v[8:11], v[178:181], v[218:221], v[8:11]
	v_mfma_f32_16x16x32_bf16 v[4:7], v[186:189], v[218:221], v[4:7]
	v_mfma_f32_16x16x32_bf16 v[56:59], v[182:185], v[198:201], v[56:59]
	v_mfma_f32_16x16x32_bf16 v[52:55], v[190:193], v[198:201], v[52:55]
	v_mfma_f32_16x16x32_bf16 v[40:43], v[182:185], v[206:209], v[40:43]
	v_mfma_f32_16x16x32_bf16 v[36:39], v[190:193], v[206:209], v[36:39]
	v_mfma_f32_16x16x32_bf16 v[24:27], v[182:185], v[214:217], v[24:27]
	v_mfma_f32_16x16x32_bf16 v[20:23], v[190:193], v[214:217], v[20:23]
	v_mfma_f32_16x16x32_bf16 v[8:11], v[182:185], v[222:225], v[8:11]
	v_mfma_f32_16x16x32_bf16 v[4:7], v[190:193], v[222:225], v[4:7]
	s_barrier
	s_add_i32 s49, s49, 2
	s_add_u32 s22, s22, 0x100
	s_addc_u32 s23, s23, 0
	s_add_u32 s47, s47, 0x100
	s_addc_u32 s48, s48, 0
	s_cmp_gt_u32 s49, 13
	s_cbranch_scc0 .LBB0_842
	s_branch .Lpeel_exit4
